# first K-iteration of all six GEMM mainloops peeled with inline-constant 0 as MFMA C: removes the 128 accumulator-zeroing v_mov per tile and wave
# baseline (speedup 1.0000x reference)
.LBB0_503:
	s_ashr_i32 s13, s12, 31
	s_lshl_b64 s[14:15], s[12:13], 20
	v_readlane_b32 s16, v234, 22
	v_readlane_b32 s17, v234, 23
	s_add_u32 s14, s16, s14
	s_addc_u32 s15, s17, s15
	s_and_b64 s[16:17], s[0:1], exec
	s_cselect_b32 s13, s15, s21
	s_cselect_b32 s42, s14, s20
	s_ashr_i32 s3, s2, 31
	s_lshl_b64 s[16:17], s[2:3], 20
	s_add_u32 s16, s10, s16
	s_addc_u32 s17, s11, s17
	s_and_b64 s[24:25], s[0:1], exec
	s_cselect_b32 s3, s17, s23
	s_cselect_b32 s43, s16, s22
	s_add_u32 s20, s20, 0x80080
	s_addc_u32 s21, s21, 0
	s_add_u32 s44, s22, 0x100
	s_addc_u32 s45, s23, 0
	s_mov_b32 s46, -2
	ds_read_b128 v[144:147], v153
	ds_read_b128 v[158:161], v153 offset:1024
	ds_read_b128 v[162:165], v153 offset:2048
	ds_read_b128 v[166:169], v153 offset:3072
	ds_read_b128 v[170:173], v154
	ds_read_b128 v[174:177], v154 offset:1024
	ds_read_b128 v[178:181], v154 offset:2048
	ds_read_b128 v[184:187], v154 offset:3072
	s_add_u32 s22, s20, 0xfff80080
	s_addc_u32 s23, s21, -1
	s_cmp_eq_u32 s46, 28
	s_cselect_b32 s25, s13, s23
	s_cselect_b32 s24, s42, s22
	s_cselect_b32 s23, s3, s45
	s_cselect_b32 s22, s43, s44
	v_lshl_add_u64 v[148:149], s[20:21], 0, v[136:137]
	s_add_i32 m0, s28, 0xc000
	ds_read_b128 v[190:193], v155
	ds_read_b128 v[194:197], v155 offset:1024
	ds_read_b128 v[198:201], v155 offset:2048
	ds_read_b128 v[202:205], v155 offset:3072
	ds_read_b128 v[206:209], v155 offset:4096
	ds_read_b128 v[210:213], v155 offset:5120
	ds_read_b128 v[214:217], v155 offset:6144
	ds_read_b128 v[218:221], v155 offset:7168
	global_load_lds_dwordx4 v[148:149], off
	v_lshl_add_u64 v[148:149], s[20:21], 0, v[138:139]
	s_add_i32 m0, s28, 0xe000
	s_nop 0
	global_load_lds_dwordx4 v[148:149], off
	s_waitcnt vmcnt(8)
	s_waitcnt lgkmcnt(0)
	s_barrier
	s_setprio 1
	s_waitcnt lgkmcnt(0)
	v_mfma_f32_16x16x32_bf16 v[124:127], v[144:147], v[190:193], 0
	v_mfma_f32_16x16x32_bf16 v[116:119], v[162:165], v[190:193], 0
	v_mfma_f32_16x16x32_bf16 v[108:111], v[144:147], v[198:201], 0
	v_mfma_f32_16x16x32_bf16 v[100:103], v[162:165], v[198:201], 0
	v_mfma_f32_16x16x32_bf16 v[92:95], v[144:147], v[206:209], 0
	v_mfma_f32_16x16x32_bf16 v[84:87], v[162:165], v[206:209], 0
	v_mfma_f32_16x16x32_bf16 v[76:79], v[144:147], v[214:217], 0
	v_mfma_f32_16x16x32_bf16 v[68:71], v[162:165], v[214:217], 0
	v_mfma_f32_16x16x32_bf16 v[124:127], v[158:161], v[194:197], v[124:127]
	v_mfma_f32_16x16x32_bf16 v[116:119], v[166:169], v[194:197], v[116:119]
	v_mfma_f32_16x16x32_bf16 v[108:111], v[158:161], v[202:205], v[108:111]
	v_mfma_f32_16x16x32_bf16 v[100:103], v[166:169], v[202:205], v[100:103]
	v_mfma_f32_16x16x32_bf16 v[92:95], v[158:161], v[210:213], v[92:95]
	v_mfma_f32_16x16x32_bf16 v[84:87], v[166:169], v[210:213], v[84:87]
	v_mfma_f32_16x16x32_bf16 v[76:79], v[158:161], v[218:221], v[76:79]
	v_mfma_f32_16x16x32_bf16 v[68:71], v[166:169], v[218:221], v[68:71]
	s_setprio 0
	s_setprio 1
	v_mfma_f32_16x16x32_bf16 v[120:123], v[170:173], v[190:193], 0
	v_mfma_f32_16x16x32_bf16 v[112:115], v[178:181], v[190:193], 0
	v_mfma_f32_16x16x32_bf16 v[104:107], v[170:173], v[198:201], 0
	v_mfma_f32_16x16x32_bf16 v[96:99], v[178:181], v[198:201], 0
	v_mfma_f32_16x16x32_bf16 v[88:91], v[170:173], v[206:209], 0
	v_mfma_f32_16x16x32_bf16 v[80:83], v[178:181], v[206:209], 0
	v_mfma_f32_16x16x32_bf16 v[72:75], v[170:173], v[214:217], 0
	v_mfma_f32_16x16x32_bf16 v[64:67], v[178:181], v[214:217], 0
	v_mfma_f32_16x16x32_bf16 v[120:123], v[174:177], v[194:197], v[120:123]
	v_mfma_f32_16x16x32_bf16 v[112:115], v[184:187], v[194:197], v[112:115]
	v_mfma_f32_16x16x32_bf16 v[104:107], v[174:177], v[202:205], v[104:107]
	v_mfma_f32_16x16x32_bf16 v[96:99], v[184:187], v[202:205], v[96:99]
	v_mfma_f32_16x16x32_bf16 v[88:91], v[174:177], v[210:213], v[88:91]
	v_mfma_f32_16x16x32_bf16 v[80:83], v[184:187], v[210:213], v[80:83]
	v_mfma_f32_16x16x32_bf16 v[72:75], v[174:177], v[218:221], v[72:75]
	v_mfma_f32_16x16x32_bf16 v[64:67], v[184:187], v[218:221], v[64:67]
	s_setprio 0
	s_barrier
	s_add_i32 s47, s38, s27
	v_lshl_add_u64 v[148:149], s[22:23], 0, v[130:131]
	s_mov_b32 m0, s47
	ds_read_b128 v[190:193], v155 offset:16384
	ds_read_b128 v[194:197], v155 offset:17408
	ds_read_b128 v[198:201], v155 offset:18432
	ds_read_b128 v[202:205], v155 offset:19456
	ds_read_b128 v[206:209], v155 offset:20480
	ds_read_b128 v[210:213], v155 offset:21504
	ds_read_b128 v[214:217], v155 offset:22528
	ds_read_b128 v[218:221], v155 offset:23552
	global_load_lds_dwordx4 v[148:149], off
	s_add_i32 m0, s47, 0x2000
	s_add_u32 s48, s22, 0x80000
	v_lshl_add_u64 v[222:223], s[22:23], 0, v[134:135]
	s_addc_u32 s49, s23, 0
	s_add_i32 s47, s39, s27
	global_load_lds_dwordx4 v[222:223], off
	v_lshl_add_u64 v[224:225], s[48:49], 0, v[130:131]
	s_mov_b32 m0, s47
	v_lshl_add_u64 v[226:227], s[24:25], 0, v[132:133]
	global_load_lds_dwordx4 v[224:225], off
	v_lshl_add_u64 v[224:225], s[48:49], 0, v[134:135]
	s_add_i32 m0, s47, 0x2000
	s_nop 0
	global_load_lds_dwordx4 v[224:225], off
	v_lshl_add_u64 v[224:225], s[24:25], 0, v[128:129]
	s_mov_b32 m0, s28
	s_nop 0
	global_load_lds_dwordx4 v[224:225], off
	s_mov_b32 m0, s29
	s_nop 0
	global_load_lds_dwordx4 v[226:227], off
	s_waitcnt vmcnt(8)
	s_waitcnt lgkmcnt(0)
	s_barrier
	s_setprio 1
	s_waitcnt lgkmcnt(0)
	v_mfma_f32_16x16x32_bf16 v[60:63], v[144:147], v[190:193], 0
	v_mfma_f32_16x16x32_bf16 v[52:55], v[162:165], v[190:193], 0
	v_mfma_f32_16x16x32_bf16 v[44:47], v[144:147], v[198:201], 0
	v_mfma_f32_16x16x32_bf16 v[36:39], v[162:165], v[198:201], 0
	v_mfma_f32_16x16x32_bf16 v[28:31], v[144:147], v[206:209], 0
	v_mfma_f32_16x16x32_bf16 v[20:23], v[162:165], v[206:209], 0
	v_mfma_f32_16x16x32_bf16 v[12:15], v[144:147], v[214:217], 0
	v_mfma_f32_16x16x32_bf16 v[4:7], v[162:165], v[214:217], 0
	v_mfma_f32_16x16x32_bf16 v[60:63], v[158:161], v[194:197], v[60:63]
	v_mfma_f32_16x16x32_bf16 v[52:55], v[166:169], v[194:197], v[52:55]
	v_mfma_f32_16x16x32_bf16 v[44:47], v[158:161], v[202:205], v[44:47]
	v_mfma_f32_16x16x32_bf16 v[36:39], v[166:169], v[202:205], v[36:39]
	v_mfma_f32_16x16x32_bf16 v[28:31], v[158:161], v[210:213], v[28:31]
	v_mfma_f32_16x16x32_bf16 v[20:23], v[166:169], v[210:213], v[20:23]
	v_mfma_f32_16x16x32_bf16 v[12:15], v[158:161], v[218:221], v[12:15]
	v_mfma_f32_16x16x32_bf16 v[4:7], v[166:169], v[218:221], v[4:7]
	s_setprio 0
	s_setprio 1
	v_mfma_f32_16x16x32_bf16 v[56:59], v[170:173], v[190:193], 0
	v_mfma_f32_16x16x32_bf16 v[48:51], v[178:181], v[190:193], 0
	v_mfma_f32_16x16x32_bf16 v[40:43], v[170:173], v[198:201], 0
	v_mfma_f32_16x16x32_bf16 v[32:35], v[178:181], v[198:201], 0
	v_mfma_f32_16x16x32_bf16 v[24:27], v[170:173], v[206:209], 0
	v_mfma_f32_16x16x32_bf16 v[16:19], v[178:181], v[206:209], 0
	v_mfma_f32_16x16x32_bf16 v[8:11], v[170:173], v[214:217], 0
	v_mfma_f32_16x16x32_bf16 v[0:3], v[178:181], v[214:217], 0
	v_mfma_f32_16x16x32_bf16 v[56:59], v[174:177], v[194:197], v[56:59]
	v_mfma_f32_16x16x32_bf16 v[48:51], v[184:187], v[194:197], v[48:51]
	v_mfma_f32_16x16x32_bf16 v[40:43], v[174:177], v[202:205], v[40:43]
	v_mfma_f32_16x16x32_bf16 v[32:35], v[184:187], v[202:205], v[32:35]
	v_mfma_f32_16x16x32_bf16 v[24:27], v[174:177], v[210:213], v[24:27]
	v_mfma_f32_16x16x32_bf16 v[16:19], v[184:187], v[210:213], v[16:19]
	v_mfma_f32_16x16x32_bf16 v[8:11], v[174:177], v[218:221], v[8:11]
	v_mfma_f32_16x16x32_bf16 v[0:3], v[184:187], v[218:221], v[0:3]
	s_setprio 0
	s_barrier
	s_add_i32 s47, 0, 0x18000
	v_add_u32_e32 v157, s47, v151
	s_add_i32 s48, 0, 0x1c000
	ds_read_b128 v[144:147], v157
	ds_read_b128 v[158:161], v157 offset:1024
	ds_read_b128 v[162:165], v157 offset:2048
	ds_read_b128 v[166:169], v157 offset:3072
	v_add_u32_e32 v157, s48, v151
	ds_read_b128 v[170:173], v157
	ds_read_b128 v[174:177], v157 offset:1024
	ds_read_b128 v[178:181], v157 offset:2048
	ds_read_b128 v[184:187], v157 offset:3072
	s_add_u32 s24, s24, 0x80000
	s_addc_u32 s25, s25, 0
	s_mov_b32 m0, s30
	v_lshl_add_u64 v[228:229], s[24:25], 0, v[128:129]
	ds_read_b128 v[190:193], v155 offset:32768
	ds_read_b128 v[194:197], v155 offset:33792
	ds_read_b128 v[198:201], v155 offset:34816
	ds_read_b128 v[202:205], v155 offset:35840
	ds_read_b128 v[206:209], v155 offset:36864
	ds_read_b128 v[210:213], v155 offset:37888
	ds_read_b128 v[214:217], v155 offset:38912
	ds_read_b128 v[218:221], v155 offset:39936
	global_load_lds_dwordx4 v[228:229], off
	v_lshl_add_u64 v[228:229], s[24:25], 0, v[132:133]
	s_mov_b32 m0, s31
	s_nop 0
	global_load_lds_dwordx4 v[228:229], off
	s_waitcnt vmcnt(8)
	s_waitcnt lgkmcnt(0)
	s_barrier
	s_setprio 1
	s_waitcnt lgkmcnt(0)
	v_mfma_f32_16x16x32_bf16 v[124:127], v[144:147], v[190:193], v[124:127]
	v_mfma_f32_16x16x32_bf16 v[116:119], v[162:165], v[190:193], v[116:119]
	v_mfma_f32_16x16x32_bf16 v[108:111], v[144:147], v[198:201], v[108:111]
	v_mfma_f32_16x16x32_bf16 v[100:103], v[162:165], v[198:201], v[100:103]
	v_mfma_f32_16x16x32_bf16 v[92:95], v[144:147], v[206:209], v[92:95]
	v_mfma_f32_16x16x32_bf16 v[84:87], v[162:165], v[206:209], v[84:87]
	v_mfma_f32_16x16x32_bf16 v[76:79], v[144:147], v[214:217], v[76:79]
	v_mfma_f32_16x16x32_bf16 v[68:71], v[162:165], v[214:217], v[68:71]
	v_mfma_f32_16x16x32_bf16 v[124:127], v[158:161], v[194:197], v[124:127]
	v_mfma_f32_16x16x32_bf16 v[116:119], v[166:169], v[194:197], v[116:119]
	v_mfma_f32_16x16x32_bf16 v[108:111], v[158:161], v[202:205], v[108:111]
	v_mfma_f32_16x16x32_bf16 v[100:103], v[166:169], v[202:205], v[100:103]
	v_mfma_f32_16x16x32_bf16 v[92:95], v[158:161], v[210:213], v[92:95]
	v_mfma_f32_16x16x32_bf16 v[84:87], v[166:169], v[210:213], v[84:87]
	v_mfma_f32_16x16x32_bf16 v[76:79], v[158:161], v[218:221], v[76:79]
	v_mfma_f32_16x16x32_bf16 v[68:71], v[166:169], v[218:221], v[68:71]
	s_setprio 0
	s_setprio 1
	v_mfma_f32_16x16x32_bf16 v[120:123], v[170:173], v[190:193], v[120:123]
	v_mfma_f32_16x16x32_bf16 v[112:115], v[178:181], v[190:193], v[112:115]
	v_mfma_f32_16x16x32_bf16 v[104:107], v[170:173], v[198:201], v[104:107]
	v_mfma_f32_16x16x32_bf16 v[96:99], v[178:181], v[198:201], v[96:99]
	v_mfma_f32_16x16x32_bf16 v[88:91], v[170:173], v[206:209], v[88:91]
	v_mfma_f32_16x16x32_bf16 v[80:83], v[178:181], v[206:209], v[80:83]
	v_mfma_f32_16x16x32_bf16 v[72:75], v[170:173], v[214:217], v[72:75]
	v_mfma_f32_16x16x32_bf16 v[64:67], v[178:181], v[214:217], v[64:67]
	v_mfma_f32_16x16x32_bf16 v[120:123], v[174:177], v[194:197], v[120:123]
	v_mfma_f32_16x16x32_bf16 v[112:115], v[184:187], v[194:197], v[112:115]
	v_mfma_f32_16x16x32_bf16 v[104:107], v[174:177], v[202:205], v[104:107]
	v_mfma_f32_16x16x32_bf16 v[96:99], v[184:187], v[202:205], v[96:99]
	v_mfma_f32_16x16x32_bf16 v[88:91], v[174:177], v[210:213], v[88:91]
	v_mfma_f32_16x16x32_bf16 v[80:83], v[184:187], v[210:213], v[80:83]
	v_mfma_f32_16x16x32_bf16 v[72:75], v[174:177], v[218:221], v[72:75]
	v_mfma_f32_16x16x32_bf16 v[64:67], v[184:187], v[218:221], v[64:67]
	s_setprio 0
	s_barrier
	s_add_i32 s24, s47, s27
	v_lshl_add_u64 v[148:149], v[148:149], 0, s[6:7]
	s_mov_b32 m0, s24
	ds_read_b128 v[190:193], v155 offset:49152
	ds_read_b128 v[194:197], v155 offset:50176
	ds_read_b128 v[198:201], v155 offset:51200
	ds_read_b128 v[202:205], v155 offset:52224
	ds_read_b128 v[206:209], v155 offset:53248
	ds_read_b128 v[210:213], v155 offset:54272
	ds_read_b128 v[214:217], v155 offset:55296
	ds_read_b128 v[218:221], v155 offset:56320
	global_load_lds_dwordx4 v[148:149], off
	s_add_i32 m0, s24, 0x2000
	s_add_u32 s22, s22, 0x80080
	v_lshl_add_u64 v[148:149], v[222:223], 0, s[6:7]
	s_addc_u32 s23, s23, 0
	s_add_i32 s24, s48, s27
	global_load_lds_dwordx4 v[148:149], off
	v_lshl_add_u64 v[148:149], s[22:23], 0, v[130:131]
	s_mov_b32 m0, s24
	s_nop 0
	global_load_lds_dwordx4 v[148:149], off
	v_lshl_add_u64 v[148:149], s[22:23], 0, v[134:135]
	s_add_i32 m0, s24, 0x2000
	s_nop 0
	global_load_lds_dwordx4 v[148:149], off
	v_lshl_add_u64 v[148:149], v[224:225], 0, s[6:7]
	s_mov_b32 m0, s34
	s_nop 0
	global_load_lds_dwordx4 v[148:149], off
	v_lshl_add_u64 v[148:149], v[226:227], 0, s[6:7]
	s_mov_b32 m0, s35
	s_nop 0
	global_load_lds_dwordx4 v[148:149], off
	s_waitcnt vmcnt(8)
	s_waitcnt lgkmcnt(0)
	s_barrier
	s_setprio 1
	s_waitcnt lgkmcnt(0)
	v_mfma_f32_16x16x32_bf16 v[60:63], v[144:147], v[190:193], v[60:63]
	v_mfma_f32_16x16x32_bf16 v[52:55], v[162:165], v[190:193], v[52:55]
	v_mfma_f32_16x16x32_bf16 v[44:47], v[144:147], v[198:201], v[44:47]
	v_mfma_f32_16x16x32_bf16 v[36:39], v[162:165], v[198:201], v[36:39]
	v_mfma_f32_16x16x32_bf16 v[28:31], v[144:147], v[206:209], v[28:31]
	v_mfma_f32_16x16x32_bf16 v[20:23], v[162:165], v[206:209], v[20:23]
	v_mfma_f32_16x16x32_bf16 v[12:15], v[144:147], v[214:217], v[12:15]
	v_mfma_f32_16x16x32_bf16 v[4:7], v[162:165], v[214:217], v[4:7]
	v_mfma_f32_16x16x32_bf16 v[60:63], v[158:161], v[194:197], v[60:63]
	v_mfma_f32_16x16x32_bf16 v[52:55], v[166:169], v[194:197], v[52:55]
	v_mfma_f32_16x16x32_bf16 v[44:47], v[158:161], v[202:205], v[44:47]
	v_mfma_f32_16x16x32_bf16 v[36:39], v[166:169], v[202:205], v[36:39]
	v_mfma_f32_16x16x32_bf16 v[28:31], v[158:161], v[210:213], v[28:31]
	v_mfma_f32_16x16x32_bf16 v[20:23], v[166:169], v[210:213], v[20:23]
	v_mfma_f32_16x16x32_bf16 v[12:15], v[158:161], v[218:221], v[12:15]
	v_mfma_f32_16x16x32_bf16 v[4:7], v[166:169], v[218:221], v[4:7]
	s_setprio 0
	s_setprio 1
	v_mfma_f32_16x16x32_bf16 v[56:59], v[170:173], v[190:193], v[56:59]
	v_mfma_f32_16x16x32_bf16 v[48:51], v[178:181], v[190:193], v[48:51]
	s_add_i32 s46, s46, 2
	s_add_u32 s20, s20, 0x100
	s_addc_u32 s21, s21, 0
	s_add_u32 s44, s44, 0x100
	s_addc_u32 s45, s45, 0
	s_cmp_gt_u32 s46, 29
	v_mfma_f32_16x16x32_bf16 v[40:43], v[170:173], v[198:201], v[40:43]
	v_mfma_f32_16x16x32_bf16 v[32:35], v[178:181], v[198:201], v[32:35]
	v_mfma_f32_16x16x32_bf16 v[24:27], v[170:173], v[206:209], v[24:27]
	v_mfma_f32_16x16x32_bf16 v[16:19], v[178:181], v[206:209], v[16:19]
	v_mfma_f32_16x16x32_bf16 v[8:11], v[170:173], v[214:217], v[8:11]
	v_mfma_f32_16x16x32_bf16 v[0:3], v[178:181], v[214:217], v[0:3]
	v_mfma_f32_16x16x32_bf16 v[56:59], v[174:177], v[194:197], v[56:59]
	v_mfma_f32_16x16x32_bf16 v[48:51], v[184:187], v[194:197], v[48:51]
	v_mfma_f32_16x16x32_bf16 v[40:43], v[174:177], v[202:205], v[40:43]
	v_mfma_f32_16x16x32_bf16 v[32:35], v[184:187], v[202:205], v[32:35]
	v_mfma_f32_16x16x32_bf16 v[24:27], v[174:177], v[210:213], v[24:27]
	v_mfma_f32_16x16x32_bf16 v[16:19], v[184:187], v[210:213], v[16:19]
	v_mfma_f32_16x16x32_bf16 v[8:11], v[174:177], v[218:221], v[8:11]
	v_mfma_f32_16x16x32_bf16 v[0:3], v[184:187], v[218:221], v[0:3]
	s_setprio 0
	s_barrier

.LBB0_1012:
	s_add_u32 s46, s22, 0x100
	s_addc_u32 s47, s23, 0
	s_mov_b32 s48, -2
	s_waitcnt lgkmcnt(0)
	ds_read_b128 v[140:143], v149
	ds_read_b128 v[154:157], v149 offset:1024
	ds_read_b128 v[158:161], v149 offset:2048
	ds_read_b128 v[162:165], v149 offset:3072
	ds_read_b128 v[166:169], v150
	ds_read_b128 v[170:173], v150 offset:1024
	ds_read_b128 v[174:177], v150 offset:2048
	ds_read_b128 v[178:181], v150 offset:3072
	s_add_u32 s22, s20, 0x100
	s_addc_u32 s23, s21, 0
	s_cmpk_eq_i32 s48, 0x54
	s_cselect_b32 s27, s1, s23
	s_cselect_b32 s26, s0, s22
	s_cselect_b32 s25, s3, s47
	s_cselect_b32 s24, s2, s46
	v_lshl_add_u64 v[144:145], s[20:21], 0, v[132:133]
	s_add_i32 m0, s29, 0xc000
	ds_read_b128 v[184:187], v151
	ds_read_b128 v[190:193], v151 offset:1024
	ds_read_b128 v[194:197], v151 offset:2048
	ds_read_b128 v[198:201], v151 offset:3072
	ds_read_b128 v[202:205], v151 offset:4096
	ds_read_b128 v[206:209], v151 offset:5120
	ds_read_b128 v[210:213], v151 offset:6144
	ds_read_b128 v[214:217], v151 offset:7168
	global_load_lds_dwordx4 v[144:145], off
	v_lshl_add_u64 v[144:145], s[20:21], 0, v[134:135]
	s_add_i32 m0, s29, 0xe000
	s_nop 0
	global_load_lds_dwordx4 v[144:145], off
	s_waitcnt vmcnt(8)
	s_waitcnt lgkmcnt(0)
	s_barrier
	s_setprio 1
	s_waitcnt lgkmcnt(0)
	v_mfma_f32_16x16x32_bf16 v[124:127], v[140:143], v[184:187], 0
	v_mfma_f32_16x16x32_bf16 v[120:123], v[158:161], v[184:187], 0
	v_mfma_f32_16x16x32_bf16 v[108:111], v[140:143], v[194:197], 0
	v_mfma_f32_16x16x32_bf16 v[104:107], v[158:161], v[194:197], 0
	v_mfma_f32_16x16x32_bf16 v[92:95], v[140:143], v[202:205], 0
	v_mfma_f32_16x16x32_bf16 v[88:91], v[158:161], v[202:205], 0
	v_mfma_f32_16x16x32_bf16 v[76:79], v[140:143], v[210:213], 0
	v_mfma_f32_16x16x32_bf16 v[72:75], v[158:161], v[210:213], 0
	v_mfma_f32_16x16x32_bf16 v[124:127], v[154:157], v[190:193], v[124:127]
	v_mfma_f32_16x16x32_bf16 v[120:123], v[162:165], v[190:193], v[120:123]
	v_mfma_f32_16x16x32_bf16 v[108:111], v[154:157], v[198:201], v[108:111]
	v_mfma_f32_16x16x32_bf16 v[104:107], v[162:165], v[198:201], v[104:107]
	v_mfma_f32_16x16x32_bf16 v[92:95], v[154:157], v[206:209], v[92:95]
	v_mfma_f32_16x16x32_bf16 v[88:91], v[162:165], v[206:209], v[88:91]
	v_mfma_f32_16x16x32_bf16 v[76:79], v[154:157], v[214:217], v[76:79]
	v_mfma_f32_16x16x32_bf16 v[72:75], v[162:165], v[214:217], v[72:75]
	s_setprio 0
	s_setprio 1
	v_mfma_f32_16x16x32_bf16 v[116:119], v[166:169], v[184:187], 0
	v_mfma_f32_16x16x32_bf16 v[112:115], v[174:177], v[184:187], 0
	v_mfma_f32_16x16x32_bf16 v[100:103], v[166:169], v[194:197], 0
	v_mfma_f32_16x16x32_bf16 v[96:99], v[174:177], v[194:197], 0
	v_mfma_f32_16x16x32_bf16 v[84:87], v[166:169], v[202:205], 0
	v_mfma_f32_16x16x32_bf16 v[80:83], v[174:177], v[202:205], 0
	v_mfma_f32_16x16x32_bf16 v[68:71], v[166:169], v[210:213], 0
	v_mfma_f32_16x16x32_bf16 v[64:67], v[174:177], v[210:213], 0
	v_mfma_f32_16x16x32_bf16 v[116:119], v[170:173], v[190:193], v[116:119]
	v_mfma_f32_16x16x32_bf16 v[112:115], v[178:181], v[190:193], v[112:115]
	v_mfma_f32_16x16x32_bf16 v[100:103], v[170:173], v[198:201], v[100:103]
	v_mfma_f32_16x16x32_bf16 v[96:99], v[178:181], v[198:201], v[96:99]
	v_mfma_f32_16x16x32_bf16 v[84:87], v[170:173], v[206:209], v[84:87]
	v_mfma_f32_16x16x32_bf16 v[80:83], v[178:181], v[206:209], v[80:83]
	v_mfma_f32_16x16x32_bf16 v[68:71], v[170:173], v[214:217], v[68:71]
	v_mfma_f32_16x16x32_bf16 v[64:67], v[178:181], v[214:217], v[64:67]
	s_setprio 0
	s_barrier
	s_add_i32 s20, s40, s28
	v_lshl_add_u64 v[144:145], s[24:25], 0, v[128:129]
	s_mov_b32 m0, s20
	ds_read_b128 v[184:187], v151 offset:16384
	ds_read_b128 v[190:193], v151 offset:17408
	ds_read_b128 v[194:197], v151 offset:18432
	ds_read_b128 v[198:201], v151 offset:19456
	ds_read_b128 v[202:205], v151 offset:20480
	ds_read_b128 v[206:209], v151 offset:21504
	ds_read_b128 v[210:213], v151 offset:22528
	ds_read_b128 v[214:217], v151 offset:23552
	global_load_lds_dwordx4 v[144:145], off
	s_add_i32 m0, s20, 0x2000
	s_add_u32 s20, s24, 0x160000
	v_lshl_add_u64 v[218:219], s[24:25], 0, v[130:131]
	s_addc_u32 s21, s25, 0
	s_add_i32 s49, s41, s28
	global_load_lds_dwordx4 v[218:219], off
	v_lshl_add_u64 v[220:221], s[20:21], 0, v[128:129]
	s_mov_b32 m0, s49
	v_lshl_add_u64 v[222:223], s[26:27], 0, v[130:131]
	global_load_lds_dwordx4 v[220:221], off
	v_lshl_add_u64 v[220:221], s[20:21], 0, v[130:131]
	s_add_i32 m0, s49, 0x2000
	s_nop 0
	global_load_lds_dwordx4 v[220:221], off
	v_lshl_add_u64 v[220:221], s[26:27], 0, v[128:129]
	s_mov_b32 m0, s29
	s_nop 0
	global_load_lds_dwordx4 v[220:221], off
	s_mov_b32 m0, s30
	s_nop 0
	global_load_lds_dwordx4 v[222:223], off
	s_waitcnt vmcnt(8)
	s_waitcnt lgkmcnt(0)
	s_barrier
	s_setprio 1
	s_waitcnt lgkmcnt(0)
	v_mfma_f32_16x16x32_bf16 v[60:63], v[140:143], v[184:187], 0
	v_mfma_f32_16x16x32_bf16 v[56:59], v[158:161], v[184:187], 0
	v_mfma_f32_16x16x32_bf16 v[44:47], v[140:143], v[194:197], 0
	v_mfma_f32_16x16x32_bf16 v[40:43], v[158:161], v[194:197], 0
	v_mfma_f32_16x16x32_bf16 v[28:31], v[140:143], v[202:205], 0
	v_mfma_f32_16x16x32_bf16 v[24:27], v[158:161], v[202:205], 0
	v_mfma_f32_16x16x32_bf16 v[12:15], v[140:143], v[210:213], 0
	v_mfma_f32_16x16x32_bf16 v[8:11], v[158:161], v[210:213], 0
	v_mfma_f32_16x16x32_bf16 v[60:63], v[154:157], v[190:193], v[60:63]
	v_mfma_f32_16x16x32_bf16 v[56:59], v[162:165], v[190:193], v[56:59]
	v_mfma_f32_16x16x32_bf16 v[44:47], v[154:157], v[198:201], v[44:47]
	v_mfma_f32_16x16x32_bf16 v[40:43], v[162:165], v[198:201], v[40:43]
	v_mfma_f32_16x16x32_bf16 v[28:31], v[154:157], v[206:209], v[28:31]
	v_mfma_f32_16x16x32_bf16 v[24:27], v[162:165], v[206:209], v[24:27]
	v_mfma_f32_16x16x32_bf16 v[12:15], v[154:157], v[214:217], v[12:15]
	v_mfma_f32_16x16x32_bf16 v[8:11], v[162:165], v[214:217], v[8:11]
	s_setprio 0
	s_setprio 1
	v_mfma_f32_16x16x32_bf16 v[52:55], v[166:169], v[184:187], 0
	v_mfma_f32_16x16x32_bf16 v[48:51], v[174:177], v[184:187], 0
	v_mfma_f32_16x16x32_bf16 v[36:39], v[166:169], v[194:197], 0
	v_mfma_f32_16x16x32_bf16 v[32:35], v[174:177], v[194:197], 0
	v_mfma_f32_16x16x32_bf16 v[20:23], v[166:169], v[202:205], 0
	v_mfma_f32_16x16x32_bf16 v[16:19], v[174:177], v[202:205], 0
	v_mfma_f32_16x16x32_bf16 v[4:7], v[166:169], v[210:213], 0
	v_mfma_f32_16x16x32_bf16 v[0:3], v[174:177], v[210:213], 0
	v_mfma_f32_16x16x32_bf16 v[52:55], v[170:173], v[190:193], v[52:55]
	v_mfma_f32_16x16x32_bf16 v[48:51], v[178:181], v[190:193], v[48:51]
	v_mfma_f32_16x16x32_bf16 v[36:39], v[170:173], v[198:201], v[36:39]
	v_mfma_f32_16x16x32_bf16 v[32:35], v[178:181], v[198:201], v[32:35]
	v_mfma_f32_16x16x32_bf16 v[20:23], v[170:173], v[206:209], v[20:23]
	v_mfma_f32_16x16x32_bf16 v[16:19], v[178:181], v[206:209], v[16:19]
	v_mfma_f32_16x16x32_bf16 v[4:7], v[170:173], v[214:217], v[4:7]
	v_mfma_f32_16x16x32_bf16 v[0:3], v[178:181], v[214:217], v[0:3]
	s_setprio 0
	s_barrier
	s_add_i32 s49, 0, 0x18000
	v_add_u32_e32 v153, s49, v147
	s_add_i32 s50, 0, 0x1c000
	ds_read_b128 v[140:143], v153
	ds_read_b128 v[154:157], v153 offset:1024
	ds_read_b128 v[158:161], v153 offset:2048
	ds_read_b128 v[162:165], v153 offset:3072
	v_add_u32_e32 v153, s50, v147
	ds_read_b128 v[166:169], v153
	ds_read_b128 v[170:173], v153 offset:1024
	ds_read_b128 v[174:177], v153 offset:2048
	ds_read_b128 v[178:181], v153 offset:3072
	s_add_u32 s20, s26, 0x160000
	s_addc_u32 s21, s27, 0
	s_mov_b32 m0, s31
	v_lshl_add_u64 v[224:225], s[20:21], 0, v[128:129]
	ds_read_b128 v[184:187], v151 offset:32768
	ds_read_b128 v[190:193], v151 offset:33792
	ds_read_b128 v[194:197], v151 offset:34816
	ds_read_b128 v[198:201], v151 offset:35840
	ds_read_b128 v[202:205], v151 offset:36864
	ds_read_b128 v[206:209], v151 offset:37888
	ds_read_b128 v[210:213], v151 offset:38912
	ds_read_b128 v[214:217], v151 offset:39936
	global_load_lds_dwordx4 v[224:225], off
	v_lshl_add_u64 v[224:225], s[20:21], 0, v[130:131]
	s_mov_b32 m0, s33
	s_nop 0
	global_load_lds_dwordx4 v[224:225], off
	s_waitcnt vmcnt(8)
	s_waitcnt lgkmcnt(0)
	s_barrier
	s_setprio 1
	s_waitcnt lgkmcnt(0)
	v_mfma_f32_16x16x32_bf16 v[124:127], v[140:143], v[184:187], v[124:127]
	v_mfma_f32_16x16x32_bf16 v[120:123], v[158:161], v[184:187], v[120:123]
	v_mfma_f32_16x16x32_bf16 v[108:111], v[140:143], v[194:197], v[108:111]
	v_mfma_f32_16x16x32_bf16 v[104:107], v[158:161], v[194:197], v[104:107]
	v_mfma_f32_16x16x32_bf16 v[92:95], v[140:143], v[202:205], v[92:95]
	v_mfma_f32_16x16x32_bf16 v[88:91], v[158:161], v[202:205], v[88:91]
	v_mfma_f32_16x16x32_bf16 v[76:79], v[140:143], v[210:213], v[76:79]
	v_mfma_f32_16x16x32_bf16 v[72:75], v[158:161], v[210:213], v[72:75]
	v_mfma_f32_16x16x32_bf16 v[124:127], v[154:157], v[190:193], v[124:127]
	v_mfma_f32_16x16x32_bf16 v[120:123], v[162:165], v[190:193], v[120:123]
	v_mfma_f32_16x16x32_bf16 v[108:111], v[154:157], v[198:201], v[108:111]
	v_mfma_f32_16x16x32_bf16 v[104:107], v[162:165], v[198:201], v[104:107]
	v_mfma_f32_16x16x32_bf16 v[92:95], v[154:157], v[206:209], v[92:95]
	v_mfma_f32_16x16x32_bf16 v[88:91], v[162:165], v[206:209], v[88:91]
	v_mfma_f32_16x16x32_bf16 v[76:79], v[154:157], v[214:217], v[76:79]
	v_mfma_f32_16x16x32_bf16 v[72:75], v[162:165], v[214:217], v[72:75]
	s_setprio 0
	s_setprio 1
	v_mfma_f32_16x16x32_bf16 v[116:119], v[166:169], v[184:187], v[116:119]
	v_mfma_f32_16x16x32_bf16 v[112:115], v[174:177], v[184:187], v[112:115]
	v_mfma_f32_16x16x32_bf16 v[100:103], v[166:169], v[194:197], v[100:103]
	v_mfma_f32_16x16x32_bf16 v[96:99], v[174:177], v[194:197], v[96:99]
	v_mfma_f32_16x16x32_bf16 v[84:87], v[166:169], v[202:205], v[84:87]
	v_mfma_f32_16x16x32_bf16 v[80:83], v[174:177], v[202:205], v[80:83]
	v_mfma_f32_16x16x32_bf16 v[68:71], v[166:169], v[210:213], v[68:71]
	v_mfma_f32_16x16x32_bf16 v[64:67], v[174:177], v[210:213], v[64:67]
	v_mfma_f32_16x16x32_bf16 v[116:119], v[170:173], v[190:193], v[116:119]
	v_mfma_f32_16x16x32_bf16 v[112:115], v[178:181], v[190:193], v[112:115]
	v_mfma_f32_16x16x32_bf16 v[100:103], v[170:173], v[198:201], v[100:103]
	v_mfma_f32_16x16x32_bf16 v[96:99], v[178:181], v[198:201], v[96:99]
	v_mfma_f32_16x16x32_bf16 v[84:87], v[170:173], v[206:209], v[84:87]
	v_mfma_f32_16x16x32_bf16 v[80:83], v[178:181], v[206:209], v[80:83]
	v_mfma_f32_16x16x32_bf16 v[68:71], v[170:173], v[214:217], v[68:71]
	v_mfma_f32_16x16x32_bf16 v[64:67], v[178:181], v[214:217], v[64:67]
	s_setprio 0
	s_barrier
	s_add_i32 s20, s49, s28
	v_lshl_add_u64 v[144:145], v[144:145], 0, s[12:13]
	s_mov_b32 m0, s20
	ds_read_b128 v[184:187], v151 offset:49152
	ds_read_b128 v[190:193], v151 offset:50176
	ds_read_b128 v[194:197], v151 offset:51200
	ds_read_b128 v[198:201], v151 offset:52224
	ds_read_b128 v[202:205], v151 offset:53248
	ds_read_b128 v[206:209], v151 offset:54272
	ds_read_b128 v[210:213], v151 offset:55296
	ds_read_b128 v[214:217], v151 offset:56320
	global_load_lds_dwordx4 v[144:145], off
	s_add_i32 m0, s20, 0x2000
	s_add_u32 s20, s24, 0x160080
	v_lshl_add_u64 v[144:145], v[218:219], 0, s[12:13]
	s_addc_u32 s21, s25, 0
	s_add_i32 s24, s50, s28
	global_load_lds_dwordx4 v[144:145], off
	v_lshl_add_u64 v[144:145], s[20:21], 0, v[128:129]
	s_mov_b32 m0, s24
	s_nop 0
	global_load_lds_dwordx4 v[144:145], off
	v_lshl_add_u64 v[144:145], s[20:21], 0, v[130:131]
	s_add_i32 m0, s24, 0x2000
	s_nop 0
	global_load_lds_dwordx4 v[144:145], off
	v_lshl_add_u64 v[144:145], v[220:221], 0, s[12:13]
	s_mov_b32 m0, s35
	s_nop 0
	global_load_lds_dwordx4 v[144:145], off
	v_lshl_add_u64 v[144:145], v[222:223], 0, s[12:13]
	s_mov_b32 m0, s36
	s_nop 0
	global_load_lds_dwordx4 v[144:145], off
	s_waitcnt vmcnt(8)
	s_waitcnt lgkmcnt(0)
	s_barrier
	s_setprio 1
	s_waitcnt lgkmcnt(0)
	v_mfma_f32_16x16x32_bf16 v[60:63], v[140:143], v[184:187], v[60:63]
	v_mfma_f32_16x16x32_bf16 v[56:59], v[158:161], v[184:187], v[56:59]
	v_mfma_f32_16x16x32_bf16 v[44:47], v[140:143], v[194:197], v[44:47]
	v_mfma_f32_16x16x32_bf16 v[40:43], v[158:161], v[194:197], v[40:43]
	v_mfma_f32_16x16x32_bf16 v[28:31], v[140:143], v[202:205], v[28:31]
	v_mfma_f32_16x16x32_bf16 v[24:27], v[158:161], v[202:205], v[24:27]
	v_mfma_f32_16x16x32_bf16 v[12:15], v[140:143], v[210:213], v[12:15]
	v_mfma_f32_16x16x32_bf16 v[8:11], v[158:161], v[210:213], v[8:11]
	v_mfma_f32_16x16x32_bf16 v[60:63], v[154:157], v[190:193], v[60:63]
	v_mfma_f32_16x16x32_bf16 v[56:59], v[162:165], v[190:193], v[56:59]
	v_mfma_f32_16x16x32_bf16 v[44:47], v[154:157], v[198:201], v[44:47]
	v_mfma_f32_16x16x32_bf16 v[40:43], v[162:165], v[198:201], v[40:43]
	v_mfma_f32_16x16x32_bf16 v[28:31], v[154:157], v[206:209], v[28:31]
	v_mfma_f32_16x16x32_bf16 v[24:27], v[162:165], v[206:209], v[24:27]
	v_mfma_f32_16x16x32_bf16 v[12:15], v[154:157], v[214:217], v[12:15]
	v_mfma_f32_16x16x32_bf16 v[8:11], v[162:165], v[214:217], v[8:11]
	s_setprio 0
	s_setprio 1
	v_mfma_f32_16x16x32_bf16 v[52:55], v[166:169], v[184:187], v[52:55]
	v_mfma_f32_16x16x32_bf16 v[48:51], v[174:177], v[184:187], v[48:51]
	s_add_i32 s48, s48, 2
	s_add_u32 s46, s46, 0x100
	s_addc_u32 s47, s47, 0
	s_cmpk_gt_u32 s48, 0x55
	s_mov_b64 s[20:21], s[22:23]
	v_mfma_f32_16x16x32_bf16 v[36:39], v[166:169], v[194:197], v[36:39]
	v_mfma_f32_16x16x32_bf16 v[32:35], v[174:177], v[194:197], v[32:35]
	v_mfma_f32_16x16x32_bf16 v[20:23], v[166:169], v[202:205], v[20:23]
	v_mfma_f32_16x16x32_bf16 v[16:19], v[174:177], v[202:205], v[16:19]
	v_mfma_f32_16x16x32_bf16 v[4:7], v[166:169], v[210:213], v[4:7]
	v_mfma_f32_16x16x32_bf16 v[0:3], v[174:177], v[210:213], v[0:3]
	v_mfma_f32_16x16x32_bf16 v[52:55], v[170:173], v[190:193], v[52:55]
	v_mfma_f32_16x16x32_bf16 v[48:51], v[178:181], v[190:193], v[48:51]
	v_mfma_f32_16x16x32_bf16 v[36:39], v[170:173], v[198:201], v[36:39]
	v_mfma_f32_16x16x32_bf16 v[32:35], v[178:181], v[198:201], v[32:35]
	v_mfma_f32_16x16x32_bf16 v[20:23], v[170:173], v[206:209], v[20:23]
	v_mfma_f32_16x16x32_bf16 v[16:19], v[178:181], v[206:209], v[16:19]
	v_mfma_f32_16x16x32_bf16 v[4:7], v[170:173], v[214:217], v[4:7]
	v_mfma_f32_16x16x32_bf16 v[0:3], v[178:181], v[214:217], v[0:3]
	s_setprio 0
	s_barrier

.LBB0_1113:
	s_ashr_i32 s29, s28, 31
	s_lshl_b64 s[30:31], s[28:29], 20
	v_readlane_b32 s34, v234, 22
	v_readlane_b32 s35, v234, 23
	s_add_u32 s30, s34, s30
	s_addc_u32 s31, s35, s31
	s_and_b64 s[34:35], s[4:5], exec
	s_cselect_b32 s1, s31, s9
	s_cselect_b32 s7, s30, s8
	s_ashr_i32 s27, s26, 31
	s_lshl_b64 s[34:35], s[26:27], 20
	s_add_u32 s34, s18, s34
	s_addc_u32 s35, s19, s35
	s_and_b64 s[38:39], s[4:5], exec
	s_cselect_b32 s27, s35, s37
	s_cselect_b32 s29, s34, s36
	s_add_u32 s8, s8, 0x80080
	s_addc_u32 s9, s9, 0
	s_add_u32 s56, s36, 0x100
	s_addc_u32 s57, s37, 0
	s_mov_b32 s58, -2
	ds_read_b128 v[146:149], v156
	ds_read_b128 v[160:163], v156 offset:1024
	ds_read_b128 v[164:167], v156 offset:2048
	ds_read_b128 v[168:171], v156 offset:3072
	ds_read_b128 v[172:175], v157
	ds_read_b128 v[176:179], v157 offset:1024
	ds_read_b128 v[184:187], v157 offset:2048
	ds_read_b128 v[190:193], v157 offset:3072
	s_add_u32 s36, s8, 0xfff80080
	s_addc_u32 s37, s9, -1
	s_cmp_eq_u32 s58, 28
	s_cselect_b32 s39, s1, s37
	s_cselect_b32 s38, s7, s36
	s_cselect_b32 s37, s27, s57
	s_cselect_b32 s36, s29, s56
	v_lshl_add_u64 v[150:151], s[8:9], 0, v[138:139]
	s_add_i32 m0, s40, 0xc000
	ds_read_b128 v[194:197], v158
	ds_read_b128 v[198:201], v158 offset:1024
	ds_read_b128 v[202:205], v158 offset:2048
	ds_read_b128 v[206:209], v158 offset:3072
	ds_read_b128 v[210:213], v158 offset:4096
	ds_read_b128 v[214:217], v158 offset:5120
	ds_read_b128 v[218:221], v158 offset:6144
	ds_read_b128 v[222:225], v158 offset:7168
	global_load_lds_dwordx4 v[150:151], off
	v_lshl_add_u64 v[150:151], s[8:9], 0, v[140:141]
	s_add_i32 m0, s40, 0xe000
	s_nop 0
	global_load_lds_dwordx4 v[150:151], off
	s_waitcnt vmcnt(8)
	s_waitcnt lgkmcnt(0)
	s_barrier
	s_setprio 1
	s_waitcnt lgkmcnt(0)
	v_mfma_f32_16x16x32_bf16 v[124:127], v[146:149], v[194:197], 0
	v_mfma_f32_16x16x32_bf16 v[120:123], v[164:167], v[194:197], 0
	v_mfma_f32_16x16x32_bf16 v[108:111], v[146:149], v[202:205], 0
	v_mfma_f32_16x16x32_bf16 v[104:107], v[164:167], v[202:205], 0
	v_mfma_f32_16x16x32_bf16 v[92:95], v[146:149], v[210:213], 0
	v_mfma_f32_16x16x32_bf16 v[88:91], v[164:167], v[210:213], 0
	v_mfma_f32_16x16x32_bf16 v[76:79], v[146:149], v[218:221], 0
	v_mfma_f32_16x16x32_bf16 v[72:75], v[164:167], v[218:221], 0
	v_mfma_f32_16x16x32_bf16 v[124:127], v[160:163], v[198:201], v[124:127]
	v_mfma_f32_16x16x32_bf16 v[120:123], v[168:171], v[198:201], v[120:123]
	v_mfma_f32_16x16x32_bf16 v[108:111], v[160:163], v[206:209], v[108:111]
	v_mfma_f32_16x16x32_bf16 v[104:107], v[168:171], v[206:209], v[104:107]
	v_mfma_f32_16x16x32_bf16 v[92:95], v[160:163], v[214:217], v[92:95]
	v_mfma_f32_16x16x32_bf16 v[88:91], v[168:171], v[214:217], v[88:91]
	v_mfma_f32_16x16x32_bf16 v[76:79], v[160:163], v[222:225], v[76:79]
	v_mfma_f32_16x16x32_bf16 v[72:75], v[168:171], v[222:225], v[72:75]
	s_setprio 0
	s_setprio 1
	v_mfma_f32_16x16x32_bf16 v[116:119], v[172:175], v[194:197], 0
	v_mfma_f32_16x16x32_bf16 v[112:115], v[184:187], v[194:197], 0
	v_mfma_f32_16x16x32_bf16 v[100:103], v[172:175], v[202:205], 0
	v_mfma_f32_16x16x32_bf16 v[96:99], v[184:187], v[202:205], 0
	v_mfma_f32_16x16x32_bf16 v[84:87], v[172:175], v[210:213], 0
	v_mfma_f32_16x16x32_bf16 v[80:83], v[184:187], v[210:213], 0
	v_mfma_f32_16x16x32_bf16 v[68:71], v[172:175], v[218:221], 0
	v_mfma_f32_16x16x32_bf16 v[64:67], v[184:187], v[218:221], 0
	v_mfma_f32_16x16x32_bf16 v[116:119], v[176:179], v[198:201], v[116:119]
	v_mfma_f32_16x16x32_bf16 v[112:115], v[190:193], v[198:201], v[112:115]
	v_mfma_f32_16x16x32_bf16 v[100:103], v[176:179], v[206:209], v[100:103]
	v_mfma_f32_16x16x32_bf16 v[96:99], v[190:193], v[206:209], v[96:99]
	v_mfma_f32_16x16x32_bf16 v[84:87], v[176:179], v[214:217], v[84:87]
	v_mfma_f32_16x16x32_bf16 v[80:83], v[190:193], v[214:217], v[80:83]
	v_mfma_f32_16x16x32_bf16 v[68:71], v[176:179], v[222:225], v[68:71]
	v_mfma_f32_16x16x32_bf16 v[64:67], v[190:193], v[222:225], v[64:67]
	s_setprio 0
	s_barrier
	s_add_i32 s59, s50, s33
	v_lshl_add_u64 v[150:151], s[36:37], 0, v[130:131]
	s_mov_b32 m0, s59
	ds_read_b128 v[194:197], v158 offset:16384
	ds_read_b128 v[198:201], v158 offset:17408
	ds_read_b128 v[202:205], v158 offset:18432
	ds_read_b128 v[206:209], v158 offset:19456
	ds_read_b128 v[210:213], v158 offset:20480
	ds_read_b128 v[214:217], v158 offset:21504
	ds_read_b128 v[218:221], v158 offset:22528
	ds_read_b128 v[222:225], v158 offset:23552
	global_load_lds_dwordx4 v[150:151], off
	s_add_i32 m0, s59, 0x2000
	s_add_u32 s60, s36, 0x80000
	v_lshl_add_u64 v[180:181], s[36:37], 0, v[134:135]
	s_addc_u32 s61, s37, 0
	s_add_i32 s59, s51, s33
	global_load_lds_dwordx4 v[180:181], off
	v_lshl_add_u64 v[226:227], s[60:61], 0, v[130:131]
	s_mov_b32 m0, s59
	v_lshl_add_u64 v[228:229], s[38:39], 0, v[132:133]
	global_load_lds_dwordx4 v[226:227], off
	v_lshl_add_u64 v[226:227], s[60:61], 0, v[134:135]
	s_add_i32 m0, s59, 0x2000
	s_nop 0
	global_load_lds_dwordx4 v[226:227], off
	v_lshl_add_u64 v[226:227], s[38:39], 0, v[128:129]
	s_mov_b32 m0, s40
	s_nop 0
	global_load_lds_dwordx4 v[226:227], off
	s_mov_b32 m0, s41
	s_nop 0
	global_load_lds_dwordx4 v[228:229], off
	s_waitcnt vmcnt(8)
	s_waitcnt lgkmcnt(0)
	s_barrier
	s_setprio 1
	s_waitcnt lgkmcnt(0)
	v_mfma_f32_16x16x32_bf16 v[60:63], v[146:149], v[194:197], 0
	v_mfma_f32_16x16x32_bf16 v[56:59], v[164:167], v[194:197], 0
	v_mfma_f32_16x16x32_bf16 v[44:47], v[146:149], v[202:205], 0
	v_mfma_f32_16x16x32_bf16 v[40:43], v[164:167], v[202:205], 0
	v_mfma_f32_16x16x32_bf16 v[28:31], v[146:149], v[210:213], 0
	v_mfma_f32_16x16x32_bf16 v[24:27], v[164:167], v[210:213], 0
	v_mfma_f32_16x16x32_bf16 v[12:15], v[146:149], v[218:221], 0
	v_mfma_f32_16x16x32_bf16 v[8:11], v[164:167], v[218:221], 0
	v_mfma_f32_16x16x32_bf16 v[60:63], v[160:163], v[198:201], v[60:63]
	v_mfma_f32_16x16x32_bf16 v[56:59], v[168:171], v[198:201], v[56:59]
	v_mfma_f32_16x16x32_bf16 v[44:47], v[160:163], v[206:209], v[44:47]
	v_mfma_f32_16x16x32_bf16 v[40:43], v[168:171], v[206:209], v[40:43]
	v_mfma_f32_16x16x32_bf16 v[28:31], v[160:163], v[214:217], v[28:31]
	v_mfma_f32_16x16x32_bf16 v[24:27], v[168:171], v[214:217], v[24:27]
	v_mfma_f32_16x16x32_bf16 v[12:15], v[160:163], v[222:225], v[12:15]
	v_mfma_f32_16x16x32_bf16 v[8:11], v[168:171], v[222:225], v[8:11]
	s_setprio 0
	s_setprio 1
	v_mfma_f32_16x16x32_bf16 v[52:55], v[172:175], v[194:197], 0
	v_mfma_f32_16x16x32_bf16 v[48:51], v[184:187], v[194:197], 0
	v_mfma_f32_16x16x32_bf16 v[36:39], v[172:175], v[202:205], 0
	v_mfma_f32_16x16x32_bf16 v[32:35], v[184:187], v[202:205], 0
	v_mfma_f32_16x16x32_bf16 v[20:23], v[172:175], v[210:213], 0
	v_mfma_f32_16x16x32_bf16 v[16:19], v[184:187], v[210:213], 0
	v_mfma_f32_16x16x32_bf16 v[4:7], v[172:175], v[218:221], 0
	v_mfma_f32_16x16x32_bf16 v[0:3], v[184:187], v[218:221], 0
	v_mfma_f32_16x16x32_bf16 v[52:55], v[176:179], v[198:201], v[52:55]
	v_mfma_f32_16x16x32_bf16 v[48:51], v[190:193], v[198:201], v[48:51]
	v_mfma_f32_16x16x32_bf16 v[36:39], v[176:179], v[206:209], v[36:39]
	v_mfma_f32_16x16x32_bf16 v[32:35], v[190:193], v[206:209], v[32:35]
	v_mfma_f32_16x16x32_bf16 v[20:23], v[176:179], v[214:217], v[20:23]
	v_mfma_f32_16x16x32_bf16 v[16:19], v[190:193], v[214:217], v[16:19]
	v_mfma_f32_16x16x32_bf16 v[4:7], v[176:179], v[222:225], v[4:7]
	v_mfma_f32_16x16x32_bf16 v[0:3], v[190:193], v[222:225], v[0:3]
	s_setprio 0
	s_barrier
	s_add_i32 s59, 0, 0x18000
	v_add_u32_e32 v152, s59, v154
	s_add_i32 s60, 0, 0x1c000
	ds_read_b128 v[146:149], v152
	ds_read_b128 v[160:163], v152 offset:1024
	ds_read_b128 v[164:167], v152 offset:2048
	ds_read_b128 v[168:171], v152 offset:3072
	v_add_u32_e32 v152, s60, v154
	ds_read_b128 v[172:175], v152
	ds_read_b128 v[176:179], v152 offset:1024
	ds_read_b128 v[184:187], v152 offset:2048
	ds_read_b128 v[190:193], v152 offset:3072
	s_add_u32 s38, s38, 0x80000
	s_addc_u32 s39, s39, 0
	s_mov_b32 m0, s42
	v_lshl_add_u64 v[230:231], s[38:39], 0, v[128:129]
	ds_read_b128 v[194:197], v158 offset:32768
	ds_read_b128 v[198:201], v158 offset:33792
	ds_read_b128 v[202:205], v158 offset:34816
	ds_read_b128 v[206:209], v158 offset:35840
	ds_read_b128 v[210:213], v158 offset:36864
	ds_read_b128 v[214:217], v158 offset:37888
	ds_read_b128 v[218:221], v158 offset:38912
	ds_read_b128 v[222:225], v158 offset:39936
	global_load_lds_dwordx4 v[230:231], off
	v_lshl_add_u64 v[230:231], s[38:39], 0, v[132:133]
	s_mov_b32 m0, s43
	s_nop 0
	global_load_lds_dwordx4 v[230:231], off
	s_waitcnt vmcnt(8)
	s_waitcnt lgkmcnt(0)
	s_barrier
	s_setprio 1
	s_waitcnt lgkmcnt(0)
	v_mfma_f32_16x16x32_bf16 v[124:127], v[146:149], v[194:197], v[124:127]
	v_mfma_f32_16x16x32_bf16 v[120:123], v[164:167], v[194:197], v[120:123]
	v_mfma_f32_16x16x32_bf16 v[108:111], v[146:149], v[202:205], v[108:111]
	v_mfma_f32_16x16x32_bf16 v[104:107], v[164:167], v[202:205], v[104:107]
	v_mfma_f32_16x16x32_bf16 v[92:95], v[146:149], v[210:213], v[92:95]
	v_mfma_f32_16x16x32_bf16 v[88:91], v[164:167], v[210:213], v[88:91]
	v_mfma_f32_16x16x32_bf16 v[76:79], v[146:149], v[218:221], v[76:79]
	v_mfma_f32_16x16x32_bf16 v[72:75], v[164:167], v[218:221], v[72:75]
	v_mfma_f32_16x16x32_bf16 v[124:127], v[160:163], v[198:201], v[124:127]
	v_mfma_f32_16x16x32_bf16 v[120:123], v[168:171], v[198:201], v[120:123]
	v_mfma_f32_16x16x32_bf16 v[108:111], v[160:163], v[206:209], v[108:111]
	v_mfma_f32_16x16x32_bf16 v[104:107], v[168:171], v[206:209], v[104:107]
	v_mfma_f32_16x16x32_bf16 v[92:95], v[160:163], v[214:217], v[92:95]
	v_mfma_f32_16x16x32_bf16 v[88:91], v[168:171], v[214:217], v[88:91]
	v_mfma_f32_16x16x32_bf16 v[76:79], v[160:163], v[222:225], v[76:79]
	v_mfma_f32_16x16x32_bf16 v[72:75], v[168:171], v[222:225], v[72:75]
	s_setprio 0
	s_setprio 1
	v_mfma_f32_16x16x32_bf16 v[116:119], v[172:175], v[194:197], v[116:119]
	v_mfma_f32_16x16x32_bf16 v[112:115], v[184:187], v[194:197], v[112:115]
	v_mfma_f32_16x16x32_bf16 v[100:103], v[172:175], v[202:205], v[100:103]
	v_mfma_f32_16x16x32_bf16 v[96:99], v[184:187], v[202:205], v[96:99]
	v_mfma_f32_16x16x32_bf16 v[84:87], v[172:175], v[210:213], v[84:87]
	v_mfma_f32_16x16x32_bf16 v[80:83], v[184:187], v[210:213], v[80:83]
	v_mfma_f32_16x16x32_bf16 v[68:71], v[172:175], v[218:221], v[68:71]
	v_mfma_f32_16x16x32_bf16 v[64:67], v[184:187], v[218:221], v[64:67]
	v_mfma_f32_16x16x32_bf16 v[116:119], v[176:179], v[198:201], v[116:119]
	v_mfma_f32_16x16x32_bf16 v[112:115], v[190:193], v[198:201], v[112:115]
	v_mfma_f32_16x16x32_bf16 v[100:103], v[176:179], v[206:209], v[100:103]
	v_mfma_f32_16x16x32_bf16 v[96:99], v[190:193], v[206:209], v[96:99]
	v_mfma_f32_16x16x32_bf16 v[84:87], v[176:179], v[214:217], v[84:87]
	v_mfma_f32_16x16x32_bf16 v[80:83], v[190:193], v[214:217], v[80:83]
	v_mfma_f32_16x16x32_bf16 v[68:71], v[176:179], v[222:225], v[68:71]
	v_mfma_f32_16x16x32_bf16 v[64:67], v[190:193], v[222:225], v[64:67]
	s_setprio 0
	s_barrier
	s_add_i32 s38, s59, s33
	v_lshl_add_u64 v[150:151], v[150:151], 0, s[20:21]
	s_mov_b32 m0, s38
	ds_read_b128 v[194:197], v158 offset:49152
	ds_read_b128 v[198:201], v158 offset:50176
	ds_read_b128 v[202:205], v158 offset:51200
	ds_read_b128 v[206:209], v158 offset:52224
	ds_read_b128 v[210:213], v158 offset:53248
	ds_read_b128 v[214:217], v158 offset:54272
	ds_read_b128 v[218:221], v158 offset:55296
	ds_read_b128 v[222:225], v158 offset:56320
	global_load_lds_dwordx4 v[150:151], off
	s_add_i32 m0, s38, 0x2000
	s_add_u32 s36, s36, 0x80080
	v_lshl_add_u64 v[150:151], v[180:181], 0, s[20:21]
	s_addc_u32 s37, s37, 0
	s_add_i32 s38, s60, s33
	global_load_lds_dwordx4 v[150:151], off
	v_lshl_add_u64 v[150:151], s[36:37], 0, v[130:131]
	s_mov_b32 m0, s38
	s_nop 0
	global_load_lds_dwordx4 v[150:151], off
	v_lshl_add_u64 v[150:151], s[36:37], 0, v[134:135]
	s_add_i32 m0, s38, 0x2000
	s_nop 0
	global_load_lds_dwordx4 v[150:151], off
	v_lshl_add_u64 v[150:151], v[226:227], 0, s[20:21]
	s_mov_b32 m0, s45
	s_nop 0
	global_load_lds_dwordx4 v[150:151], off
	v_lshl_add_u64 v[150:151], v[228:229], 0, s[20:21]
	s_mov_b32 m0, s46
	s_nop 0
	global_load_lds_dwordx4 v[150:151], off
	s_waitcnt vmcnt(8)
	s_waitcnt lgkmcnt(0)
	s_barrier
	s_setprio 1
	s_waitcnt lgkmcnt(0)
	v_mfma_f32_16x16x32_bf16 v[60:63], v[146:149], v[194:197], v[60:63]
	v_mfma_f32_16x16x32_bf16 v[56:59], v[164:167], v[194:197], v[56:59]
	v_mfma_f32_16x16x32_bf16 v[44:47], v[146:149], v[202:205], v[44:47]
	v_mfma_f32_16x16x32_bf16 v[40:43], v[164:167], v[202:205], v[40:43]
	v_mfma_f32_16x16x32_bf16 v[28:31], v[146:149], v[210:213], v[28:31]
	v_mfma_f32_16x16x32_bf16 v[24:27], v[164:167], v[210:213], v[24:27]
	v_mfma_f32_16x16x32_bf16 v[12:15], v[146:149], v[218:221], v[12:15]
	v_mfma_f32_16x16x32_bf16 v[8:11], v[164:167], v[218:221], v[8:11]
	v_mfma_f32_16x16x32_bf16 v[60:63], v[160:163], v[198:201], v[60:63]
	v_mfma_f32_16x16x32_bf16 v[56:59], v[168:171], v[198:201], v[56:59]
	v_mfma_f32_16x16x32_bf16 v[44:47], v[160:163], v[206:209], v[44:47]
	v_mfma_f32_16x16x32_bf16 v[40:43], v[168:171], v[206:209], v[40:43]
	v_mfma_f32_16x16x32_bf16 v[28:31], v[160:163], v[214:217], v[28:31]
	v_mfma_f32_16x16x32_bf16 v[24:27], v[168:171], v[214:217], v[24:27]
	v_mfma_f32_16x16x32_bf16 v[12:15], v[160:163], v[222:225], v[12:15]
	v_mfma_f32_16x16x32_bf16 v[8:11], v[168:171], v[222:225], v[8:11]
	s_setprio 0
	s_setprio 1
	v_mfma_f32_16x16x32_bf16 v[52:55], v[172:175], v[194:197], v[52:55]
	v_mfma_f32_16x16x32_bf16 v[48:51], v[184:187], v[194:197], v[48:51]
	s_add_i32 s58, s58, 2
	s_add_u32 s8, s8, 0x100
	s_addc_u32 s9, s9, 0
	s_add_u32 s56, s56, 0x100
	s_addc_u32 s57, s57, 0
	s_cmp_gt_u32 s58, 29
	v_mfma_f32_16x16x32_bf16 v[36:39], v[172:175], v[202:205], v[36:39]
	v_mfma_f32_16x16x32_bf16 v[32:35], v[184:187], v[202:205], v[32:35]
	v_mfma_f32_16x16x32_bf16 v[20:23], v[172:175], v[210:213], v[20:23]
	v_mfma_f32_16x16x32_bf16 v[16:19], v[184:187], v[210:213], v[16:19]
	v_mfma_f32_16x16x32_bf16 v[4:7], v[172:175], v[218:221], v[4:7]
	v_mfma_f32_16x16x32_bf16 v[0:3], v[184:187], v[218:221], v[0:3]
	v_mfma_f32_16x16x32_bf16 v[52:55], v[176:179], v[198:201], v[52:55]
	v_mfma_f32_16x16x32_bf16 v[48:51], v[190:193], v[198:201], v[48:51]
	v_mfma_f32_16x16x32_bf16 v[36:39], v[176:179], v[206:209], v[36:39]
	v_mfma_f32_16x16x32_bf16 v[32:35], v[190:193], v[206:209], v[32:35]
	v_mfma_f32_16x16x32_bf16 v[20:23], v[176:179], v[214:217], v[20:23]
	v_mfma_f32_16x16x32_bf16 v[16:19], v[190:193], v[214:217], v[16:19]
	v_mfma_f32_16x16x32_bf16 v[4:7], v[176:179], v[222:225], v[4:7]
	v_mfma_f32_16x16x32_bf16 v[0:3], v[190:193], v[222:225], v[0:3]
	s_setprio 0
	s_barrier

.LBB0_2211:
	s_ashr_i32 s19, s18, 31
	s_lshl_b64 s[20:21], s[18:19], 20
	s_add_u32 s20, s2, s20
	s_addc_u32 s21, s3, s21
	s_and_b64 s[22:23], s[8:9], exec
	s_cselect_b32 s19, s21, s29
	s_cselect_b32 s25, s20, s28
	s_ashr_i32 s17, s16, 31
	s_lshl_b64 s[22:23], s[16:17], 20
	s_add_u32 s22, s0, s22
	s_addc_u32 s23, s1, s23
	s_and_b64 s[34:35], s[8:9], exec
	s_cselect_b32 s17, s23, s31
	s_cselect_b32 s49, s22, s30
	s_add_u32 s50, s30, 0x100
	s_mov_b32 s56, s52
	s_addc_u32 s51, s31, 0
	s_mov_b32 s52, -2
	s_waitcnt lgkmcnt(0)
	ds_read_b128 v[140:143], v147
	ds_read_b128 v[154:157], v147 offset:1024
	ds_read_b128 v[158:161], v147 offset:2048
	ds_read_b128 v[162:165], v147 offset:3072
	ds_read_b128 v[166:169], v152
	ds_read_b128 v[170:173], v152 offset:1024
	ds_read_b128 v[174:177], v152 offset:2048
	ds_read_b128 v[178:181], v152 offset:3072
	s_add_u32 s30, s28, 0x100
	s_addc_u32 s31, s29, 0
	s_cmp_eq_u32 s52, 28
	s_cselect_b32 s37, s19, s31
	s_cselect_b32 s36, s25, s30
	s_cselect_b32 s35, s17, s51
	s_cselect_b32 s34, s49, s50
	v_lshl_add_u64 v[216:217], s[28:29], 0, v[132:133]
	s_add_i32 m0, s27, 0xc000
	ds_read_b128 v[184:187], v153
	ds_read_b128 v[188:191], v153 offset:1024
	ds_read_b128 v[192:195], v153 offset:2048
	ds_read_b128 v[196:199], v153 offset:3072
	ds_read_b128 v[200:203], v153 offset:4096
	ds_read_b128 v[204:207], v153 offset:5120
	ds_read_b128 v[208:211], v153 offset:6144
	ds_read_b128 v[212:215], v153 offset:7168
	global_load_lds_dwordx4 v[216:217], off
	v_lshl_add_u64 v[216:217], s[28:29], 0, v[134:135]
	s_add_i32 m0, s27, 0xe000
	s_nop 0
	global_load_lds_dwordx4 v[216:217], off
	s_waitcnt vmcnt(8)
	s_waitcnt lgkmcnt(0)
	s_barrier
	s_setprio 1
	s_waitcnt lgkmcnt(0)
	v_mfma_f32_16x16x32_bf16 v[124:127], v[140:143], v[184:187], 0
	v_mfma_f32_16x16x32_bf16 v[120:123], v[158:161], v[184:187], 0
	v_mfma_f32_16x16x32_bf16 v[108:111], v[140:143], v[192:195], 0
	v_mfma_f32_16x16x32_bf16 v[104:107], v[158:161], v[192:195], 0
	v_mfma_f32_16x16x32_bf16 v[92:95], v[140:143], v[200:203], 0
	v_mfma_f32_16x16x32_bf16 v[88:91], v[158:161], v[200:203], 0
	v_mfma_f32_16x16x32_bf16 v[76:79], v[140:143], v[208:211], 0
	v_mfma_f32_16x16x32_bf16 v[72:75], v[158:161], v[208:211], 0
	v_mfma_f32_16x16x32_bf16 v[124:127], v[154:157], v[188:191], v[124:127]
	v_mfma_f32_16x16x32_bf16 v[120:123], v[162:165], v[188:191], v[120:123]
	v_mfma_f32_16x16x32_bf16 v[108:111], v[154:157], v[196:199], v[108:111]
	v_mfma_f32_16x16x32_bf16 v[104:107], v[162:165], v[196:199], v[104:107]
	v_mfma_f32_16x16x32_bf16 v[92:95], v[154:157], v[204:207], v[92:95]
	v_mfma_f32_16x16x32_bf16 v[88:91], v[162:165], v[204:207], v[88:91]
	v_mfma_f32_16x16x32_bf16 v[76:79], v[154:157], v[212:215], v[76:79]
	v_mfma_f32_16x16x32_bf16 v[72:75], v[162:165], v[212:215], v[72:75]
	s_setprio 0
	s_setprio 1
	v_mfma_f32_16x16x32_bf16 v[116:119], v[166:169], v[184:187], 0
	v_mfma_f32_16x16x32_bf16 v[112:115], v[174:177], v[184:187], 0
	v_mfma_f32_16x16x32_bf16 v[100:103], v[166:169], v[192:195], 0
	v_mfma_f32_16x16x32_bf16 v[96:99], v[174:177], v[192:195], 0
	v_mfma_f32_16x16x32_bf16 v[84:87], v[166:169], v[200:203], 0
	v_mfma_f32_16x16x32_bf16 v[80:83], v[174:177], v[200:203], 0
	v_mfma_f32_16x16x32_bf16 v[68:71], v[166:169], v[208:211], 0
	v_mfma_f32_16x16x32_bf16 v[64:67], v[174:177], v[208:211], 0
	v_mfma_f32_16x16x32_bf16 v[116:119], v[170:173], v[188:191], v[116:119]
	v_mfma_f32_16x16x32_bf16 v[112:115], v[178:181], v[188:191], v[112:115]
	v_mfma_f32_16x16x32_bf16 v[100:103], v[170:173], v[196:199], v[100:103]
	v_mfma_f32_16x16x32_bf16 v[96:99], v[178:181], v[196:199], v[96:99]
	v_mfma_f32_16x16x32_bf16 v[84:87], v[170:173], v[204:207], v[84:87]
	v_mfma_f32_16x16x32_bf16 v[80:83], v[178:181], v[204:207], v[80:83]
	v_mfma_f32_16x16x32_bf16 v[68:71], v[170:173], v[212:215], v[68:71]
	v_mfma_f32_16x16x32_bf16 v[64:67], v[178:181], v[212:215], v[64:67]
	s_setprio 0
	s_barrier
	s_add_i32 s28, s47, s33
	v_lshl_add_u64 v[216:217], s[34:35], 0, v[128:129]
	s_mov_b32 m0, s28
	ds_read_b128 v[184:187], v153 offset:16384
	ds_read_b128 v[188:191], v153 offset:17408
	ds_read_b128 v[192:195], v153 offset:18432
	ds_read_b128 v[196:199], v153 offset:19456
	ds_read_b128 v[200:203], v153 offset:20480
	ds_read_b128 v[204:207], v153 offset:21504
	ds_read_b128 v[208:211], v153 offset:22528
	ds_read_b128 v[212:215], v153 offset:23552
	global_load_lds_dwordx4 v[216:217], off
	s_add_i32 m0, s28, 0x2000
	s_add_u32 s28, s34, 0x80000
	v_lshl_add_u64 v[218:219], s[34:35], 0, v[130:131]
	s_addc_u32 s29, s35, 0
	s_add_i32 s53, s48, s33
	global_load_lds_dwordx4 v[218:219], off
	v_lshl_add_u64 v[220:221], s[28:29], 0, v[128:129]
	s_mov_b32 m0, s53
	v_lshl_add_u64 v[222:223], s[36:37], 0, v[130:131]
	global_load_lds_dwordx4 v[220:221], off
	v_lshl_add_u64 v[220:221], s[28:29], 0, v[130:131]
	s_add_i32 m0, s53, 0x2000
	s_nop 0
	global_load_lds_dwordx4 v[220:221], off
	v_lshl_add_u64 v[220:221], s[36:37], 0, v[128:129]
	s_mov_b32 m0, s27
	s_nop 0
	global_load_lds_dwordx4 v[220:221], off
	s_mov_b32 m0, s38
	s_nop 0
	global_load_lds_dwordx4 v[222:223], off
	s_waitcnt vmcnt(8)
	s_waitcnt lgkmcnt(0)
	s_barrier
	s_setprio 1
	s_waitcnt lgkmcnt(0)
	v_mfma_f32_16x16x32_bf16 v[60:63], v[140:143], v[184:187], 0
	v_mfma_f32_16x16x32_bf16 v[56:59], v[158:161], v[184:187], 0
	v_mfma_f32_16x16x32_bf16 v[44:47], v[140:143], v[192:195], 0
	v_mfma_f32_16x16x32_bf16 v[40:43], v[158:161], v[192:195], 0
	v_mfma_f32_16x16x32_bf16 v[28:31], v[140:143], v[200:203], 0
	v_mfma_f32_16x16x32_bf16 v[24:27], v[158:161], v[200:203], 0
	v_mfma_f32_16x16x32_bf16 v[12:15], v[140:143], v[208:211], 0
	v_mfma_f32_16x16x32_bf16 v[8:11], v[158:161], v[208:211], 0
	v_mfma_f32_16x16x32_bf16 v[60:63], v[154:157], v[188:191], v[60:63]
	v_mfma_f32_16x16x32_bf16 v[56:59], v[162:165], v[188:191], v[56:59]
	v_mfma_f32_16x16x32_bf16 v[44:47], v[154:157], v[196:199], v[44:47]
	v_mfma_f32_16x16x32_bf16 v[40:43], v[162:165], v[196:199], v[40:43]
	v_mfma_f32_16x16x32_bf16 v[28:31], v[154:157], v[204:207], v[28:31]
	v_mfma_f32_16x16x32_bf16 v[24:27], v[162:165], v[204:207], v[24:27]
	v_mfma_f32_16x16x32_bf16 v[12:15], v[154:157], v[212:215], v[12:15]
	v_mfma_f32_16x16x32_bf16 v[8:11], v[162:165], v[212:215], v[8:11]
	s_setprio 0
	s_setprio 1
	v_mfma_f32_16x16x32_bf16 v[52:55], v[166:169], v[184:187], 0
	v_mfma_f32_16x16x32_bf16 v[48:51], v[174:177], v[184:187], 0
	v_mfma_f32_16x16x32_bf16 v[36:39], v[166:169], v[192:195], 0
	v_mfma_f32_16x16x32_bf16 v[32:35], v[174:177], v[192:195], 0
	v_mfma_f32_16x16x32_bf16 v[20:23], v[166:169], v[200:203], 0
	v_mfma_f32_16x16x32_bf16 v[16:19], v[174:177], v[200:203], 0
	v_mfma_f32_16x16x32_bf16 v[4:7], v[166:169], v[208:211], 0
	v_mfma_f32_16x16x32_bf16 v[0:3], v[174:177], v[208:211], 0
	v_mfma_f32_16x16x32_bf16 v[52:55], v[170:173], v[188:191], v[52:55]
	v_mfma_f32_16x16x32_bf16 v[48:51], v[178:181], v[188:191], v[48:51]
	v_mfma_f32_16x16x32_bf16 v[36:39], v[170:173], v[196:199], v[36:39]
	v_mfma_f32_16x16x32_bf16 v[32:35], v[178:181], v[196:199], v[32:35]
	v_mfma_f32_16x16x32_bf16 v[20:23], v[170:173], v[204:207], v[20:23]
	v_mfma_f32_16x16x32_bf16 v[16:19], v[178:181], v[204:207], v[16:19]
	v_mfma_f32_16x16x32_bf16 v[4:7], v[170:173], v[212:215], v[4:7]
	v_mfma_f32_16x16x32_bf16 v[0:3], v[178:181], v[212:215], v[0:3]
	s_setprio 0
	s_barrier
	s_add_i32 s53, 0, 0x18000
	s_add_i32 s54, 0, 0x1c000
	v_add_u32_e32 v162, s53, v145
	v_add_u32_e32 v178, s54, v145
	ds_read_b128 v[140:143], v162
	ds_read_b128 v[154:157], v162 offset:1024
	ds_read_b128 v[158:161], v162 offset:2048
	ds_read_b128 v[162:165], v162 offset:3072
	ds_read_b128 v[166:169], v178
	ds_read_b128 v[170:173], v178 offset:1024
	ds_read_b128 v[174:177], v178 offset:2048
	ds_read_b128 v[178:181], v178 offset:3072
	s_add_u32 s28, s36, 0x80000
	s_addc_u32 s29, s37, 0
	s_mov_b32 m0, s39
	v_lshl_add_u64 v[224:225], s[28:29], 0, v[128:129]
	ds_read_b128 v[184:187], v153 offset:32768
	ds_read_b128 v[188:191], v153 offset:33792
	ds_read_b128 v[192:195], v153 offset:34816
	ds_read_b128 v[196:199], v153 offset:35840
	ds_read_b128 v[200:203], v153 offset:36864
	ds_read_b128 v[204:207], v153 offset:37888
	ds_read_b128 v[208:211], v153 offset:38912
	ds_read_b128 v[212:215], v153 offset:39936
	global_load_lds_dwordx4 v[224:225], off
	v_lshl_add_u64 v[224:225], s[28:29], 0, v[130:131]
	s_mov_b32 m0, s40
	s_nop 0
	global_load_lds_dwordx4 v[224:225], off
	s_waitcnt vmcnt(8)
	s_waitcnt lgkmcnt(0)
	s_barrier
	s_setprio 1
	s_waitcnt lgkmcnt(0)
	v_mfma_f32_16x16x32_bf16 v[124:127], v[140:143], v[184:187], v[124:127]
	v_mfma_f32_16x16x32_bf16 v[120:123], v[158:161], v[184:187], v[120:123]
	v_mfma_f32_16x16x32_bf16 v[108:111], v[140:143], v[192:195], v[108:111]
	v_mfma_f32_16x16x32_bf16 v[104:107], v[158:161], v[192:195], v[104:107]
	v_mfma_f32_16x16x32_bf16 v[92:95], v[140:143], v[200:203], v[92:95]
	v_mfma_f32_16x16x32_bf16 v[88:91], v[158:161], v[200:203], v[88:91]
	v_mfma_f32_16x16x32_bf16 v[76:79], v[140:143], v[208:211], v[76:79]
	v_mfma_f32_16x16x32_bf16 v[72:75], v[158:161], v[208:211], v[72:75]
	v_mfma_f32_16x16x32_bf16 v[124:127], v[154:157], v[188:191], v[124:127]
	v_mfma_f32_16x16x32_bf16 v[120:123], v[162:165], v[188:191], v[120:123]
	v_mfma_f32_16x16x32_bf16 v[108:111], v[154:157], v[196:199], v[108:111]
	v_mfma_f32_16x16x32_bf16 v[104:107], v[162:165], v[196:199], v[104:107]
	v_mfma_f32_16x16x32_bf16 v[92:95], v[154:157], v[204:207], v[92:95]
	v_mfma_f32_16x16x32_bf16 v[88:91], v[162:165], v[204:207], v[88:91]
	v_mfma_f32_16x16x32_bf16 v[76:79], v[154:157], v[212:215], v[76:79]
	v_mfma_f32_16x16x32_bf16 v[72:75], v[162:165], v[212:215], v[72:75]
	s_setprio 0
	s_setprio 1
	v_mfma_f32_16x16x32_bf16 v[116:119], v[166:169], v[184:187], v[116:119]
	v_mfma_f32_16x16x32_bf16 v[112:115], v[174:177], v[184:187], v[112:115]
	v_mfma_f32_16x16x32_bf16 v[100:103], v[166:169], v[192:195], v[100:103]
	v_mfma_f32_16x16x32_bf16 v[96:99], v[174:177], v[192:195], v[96:99]
	v_mfma_f32_16x16x32_bf16 v[84:87], v[166:169], v[200:203], v[84:87]
	v_mfma_f32_16x16x32_bf16 v[80:83], v[174:177], v[200:203], v[80:83]
	v_mfma_f32_16x16x32_bf16 v[68:71], v[166:169], v[208:211], v[68:71]
	v_mfma_f32_16x16x32_bf16 v[64:67], v[174:177], v[208:211], v[64:67]
	v_mfma_f32_16x16x32_bf16 v[116:119], v[170:173], v[188:191], v[116:119]
	v_mfma_f32_16x16x32_bf16 v[112:115], v[178:181], v[188:191], v[112:115]
	v_mfma_f32_16x16x32_bf16 v[100:103], v[170:173], v[196:199], v[100:103]
	v_mfma_f32_16x16x32_bf16 v[96:99], v[178:181], v[196:199], v[96:99]
	v_mfma_f32_16x16x32_bf16 v[84:87], v[170:173], v[204:207], v[84:87]
	v_mfma_f32_16x16x32_bf16 v[80:83], v[178:181], v[204:207], v[80:83]
	v_mfma_f32_16x16x32_bf16 v[68:71], v[170:173], v[212:215], v[68:71]
	v_mfma_f32_16x16x32_bf16 v[64:67], v[178:181], v[212:215], v[64:67]
	s_setprio 0
	s_barrier
	s_add_i32 s28, s53, s33
	v_lshl_add_u64 v[216:217], v[216:217], 0, s[12:13]
	s_mov_b32 m0, s28
	ds_read_b128 v[184:187], v153 offset:49152
	ds_read_b128 v[188:191], v153 offset:50176
	ds_read_b128 v[192:195], v153 offset:51200
	ds_read_b128 v[196:199], v153 offset:52224
	ds_read_b128 v[200:203], v153 offset:53248
	ds_read_b128 v[204:207], v153 offset:54272
	ds_read_b128 v[208:211], v153 offset:55296
	ds_read_b128 v[212:215], v153 offset:56320
	global_load_lds_dwordx4 v[216:217], off
	s_add_i32 m0, s28, 0x2000
	s_add_u32 s28, s34, 0x80080
	v_lshl_add_u64 v[216:217], v[218:219], 0, s[12:13]
	s_addc_u32 s29, s35, 0
	s_add_i32 s34, s54, s33
	global_load_lds_dwordx4 v[216:217], off
	v_lshl_add_u64 v[216:217], s[28:29], 0, v[128:129]
	s_mov_b32 m0, s34
	s_nop 0
	global_load_lds_dwordx4 v[216:217], off
	v_lshl_add_u64 v[216:217], s[28:29], 0, v[130:131]
	s_add_i32 m0, s34, 0x2000
	s_nop 0
	global_load_lds_dwordx4 v[216:217], off
	v_lshl_add_u64 v[216:217], v[220:221], 0, s[12:13]
	s_mov_b32 m0, s42
	s_nop 0
	global_load_lds_dwordx4 v[216:217], off
	v_lshl_add_u64 v[216:217], v[222:223], 0, s[12:13]
	s_mov_b32 m0, s43
	s_nop 0
	global_load_lds_dwordx4 v[216:217], off
	s_waitcnt vmcnt(8)
	s_waitcnt lgkmcnt(0)
	s_barrier
	s_setprio 1
	s_waitcnt lgkmcnt(0)
	v_mfma_f32_16x16x32_bf16 v[60:63], v[140:143], v[184:187], v[60:63]
	v_mfma_f32_16x16x32_bf16 v[56:59], v[158:161], v[184:187], v[56:59]
	v_mfma_f32_16x16x32_bf16 v[44:47], v[140:143], v[192:195], v[44:47]
	v_mfma_f32_16x16x32_bf16 v[40:43], v[158:161], v[192:195], v[40:43]
	v_mfma_f32_16x16x32_bf16 v[28:31], v[140:143], v[200:203], v[28:31]
	v_mfma_f32_16x16x32_bf16 v[24:27], v[158:161], v[200:203], v[24:27]
	v_mfma_f32_16x16x32_bf16 v[12:15], v[140:143], v[208:211], v[12:15]
	v_mfma_f32_16x16x32_bf16 v[8:11], v[158:161], v[208:211], v[8:11]
	v_mfma_f32_16x16x32_bf16 v[60:63], v[154:157], v[188:191], v[60:63]
	v_mfma_f32_16x16x32_bf16 v[56:59], v[162:165], v[188:191], v[56:59]
	v_mfma_f32_16x16x32_bf16 v[44:47], v[154:157], v[196:199], v[44:47]
	v_mfma_f32_16x16x32_bf16 v[40:43], v[162:165], v[196:199], v[40:43]
	v_mfma_f32_16x16x32_bf16 v[28:31], v[154:157], v[204:207], v[28:31]
	v_mfma_f32_16x16x32_bf16 v[24:27], v[162:165], v[204:207], v[24:27]
	v_mfma_f32_16x16x32_bf16 v[12:15], v[154:157], v[212:215], v[12:15]
	v_mfma_f32_16x16x32_bf16 v[8:11], v[162:165], v[212:215], v[8:11]
	s_setprio 0
	s_setprio 1
	v_mfma_f32_16x16x32_bf16 v[52:55], v[166:169], v[184:187], v[52:55]
	v_mfma_f32_16x16x32_bf16 v[48:51], v[174:177], v[184:187], v[48:51]
	s_add_i32 s52, s52, 2
	s_add_u32 s50, s50, 0x100
	s_addc_u32 s51, s51, 0
	s_cmp_gt_u32 s52, 29
	s_mov_b64 s[28:29], s[30:31]
	v_mfma_f32_16x16x32_bf16 v[36:39], v[166:169], v[192:195], v[36:39]
	v_mfma_f32_16x16x32_bf16 v[32:35], v[174:177], v[192:195], v[32:35]
	v_mfma_f32_16x16x32_bf16 v[20:23], v[166:169], v[200:203], v[20:23]
	v_mfma_f32_16x16x32_bf16 v[16:19], v[174:177], v[200:203], v[16:19]
	v_mfma_f32_16x16x32_bf16 v[4:7], v[166:169], v[208:211], v[4:7]
	v_mfma_f32_16x16x32_bf16 v[0:3], v[174:177], v[208:211], v[0:3]
	v_mfma_f32_16x16x32_bf16 v[52:55], v[170:173], v[188:191], v[52:55]
	v_mfma_f32_16x16x32_bf16 v[48:51], v[178:181], v[188:191], v[48:51]
	v_mfma_f32_16x16x32_bf16 v[36:39], v[170:173], v[196:199], v[36:39]
	v_mfma_f32_16x16x32_bf16 v[32:35], v[178:181], v[196:199], v[32:35]
	v_mfma_f32_16x16x32_bf16 v[20:23], v[170:173], v[204:207], v[20:23]
	v_mfma_f32_16x16x32_bf16 v[16:19], v[178:181], v[204:207], v[16:19]
	v_mfma_f32_16x16x32_bf16 v[4:7], v[170:173], v[212:215], v[4:7]
	v_mfma_f32_16x16x32_bf16 v[0:3], v[178:181], v[212:215], v[0:3]
	s_setprio 0
	s_barrier

.LBB0_2310:
	s_ashr_i32 s15, s14, 31
	s_lshl_b64 s[16:17], s[14:15], 20
	v_readlane_b32 s18, v234, 22
	v_readlane_b32 s19, v234, 23
	s_add_u32 s16, s18, s16
	s_addc_u32 s17, s19, s17
	s_and_b64 s[18:19], s[6:7], exec
	s_cselect_b32 s15, s17, s21
	s_cselect_b32 s44, s16, s20
	s_ashr_i32 s13, s12, 31
	s_lshl_b64 s[18:19], s[12:13], 20
	s_add_u32 s18, s27, s18
	s_addc_u32 s19, s28, s19
	s_and_b64 s[24:25], s[6:7], exec
	s_cselect_b32 s13, s19, s23
	s_cselect_b32 s45, s18, s22
	s_add_u32 s20, s20, 0x80080
	s_addc_u32 s21, s21, 0
	s_add_u32 s46, s22, 0x100
	s_addc_u32 s47, s23, 0
	s_mov_b32 s48, -2
	ds_read_b128 v[144:147], v155
	ds_read_b128 v[160:163], v155 offset:1024
	ds_read_b128 v[164:167], v155 offset:2048
	ds_read_b128 v[168:171], v155 offset:3072
	ds_read_b128 v[172:175], v156
	ds_read_b128 v[176:179], v156 offset:1024
	ds_read_b128 v[184:187], v156 offset:2048
	ds_read_b128 v[188:191], v156 offset:3072
	s_add_u32 s22, s20, 0xfff80080
	s_addc_u32 s23, s21, -1
	s_cmp_eq_u32 s48, 28
	s_cselect_b32 s25, s15, s23
	s_cselect_b32 s24, s44, s22
	s_cselect_b32 s23, s13, s47
	s_cselect_b32 s22, s45, s46
	v_lshl_add_u64 v[180:181], s[20:21], 0, v[136:137]
	s_add_i32 m0, s30, 0xc000
	ds_read_b128 v[192:195], v157
	ds_read_b128 v[196:199], v157 offset:1024
	ds_read_b128 v[200:203], v157 offset:2048
	ds_read_b128 v[204:207], v157 offset:3072
	ds_read_b128 v[208:211], v157 offset:4096
	ds_read_b128 v[212:215], v157 offset:5120
	ds_read_b128 v[216:219], v157 offset:6144
	ds_read_b128 v[220:223], v157 offset:7168
	global_load_lds_dwordx4 v[180:181], off
	v_lshl_add_u64 v[180:181], s[20:21], 0, v[138:139]
	s_add_i32 m0, s30, 0xe000
	s_nop 0
	global_load_lds_dwordx4 v[180:181], off
	s_waitcnt vmcnt(8)
	s_waitcnt lgkmcnt(0)
	s_barrier
	s_setprio 1
	s_waitcnt lgkmcnt(0)
	v_mfma_f32_16x16x32_bf16 v[116:119], v[144:147], v[192:195], 0
	v_mfma_f32_16x16x32_bf16 v[112:115], v[164:167], v[192:195], 0
	v_mfma_f32_16x16x32_bf16 v[100:103], v[144:147], v[200:203], 0
	v_mfma_f32_16x16x32_bf16 v[96:99], v[164:167], v[200:203], 0
	v_mfma_f32_16x16x32_bf16 v[84:87], v[144:147], v[208:211], 0
	v_mfma_f32_16x16x32_bf16 v[80:83], v[164:167], v[208:211], 0
	v_mfma_f32_16x16x32_bf16 v[72:75], v[144:147], v[216:219], 0
	v_mfma_f32_16x16x32_bf16 v[64:67], v[164:167], v[216:219], 0
	v_mfma_f32_16x16x32_bf16 v[116:119], v[160:163], v[196:199], v[116:119]
	v_mfma_f32_16x16x32_bf16 v[112:115], v[168:171], v[196:199], v[112:115]
	v_mfma_f32_16x16x32_bf16 v[100:103], v[160:163], v[204:207], v[100:103]
	v_mfma_f32_16x16x32_bf16 v[96:99], v[168:171], v[204:207], v[96:99]
	v_mfma_f32_16x16x32_bf16 v[84:87], v[160:163], v[212:215], v[84:87]
	v_mfma_f32_16x16x32_bf16 v[80:83], v[168:171], v[212:215], v[80:83]
	v_mfma_f32_16x16x32_bf16 v[72:75], v[160:163], v[220:223], v[72:75]
	v_mfma_f32_16x16x32_bf16 v[64:67], v[168:171], v[220:223], v[64:67]
	s_setprio 0
	s_setprio 1
	v_mfma_f32_16x16x32_bf16 v[124:127], v[172:175], v[192:195], 0
	v_mfma_f32_16x16x32_bf16 v[120:123], v[184:187], v[192:195], 0
	v_mfma_f32_16x16x32_bf16 v[108:111], v[172:175], v[200:203], 0
	v_mfma_f32_16x16x32_bf16 v[104:107], v[184:187], v[200:203], 0
	v_mfma_f32_16x16x32_bf16 v[92:95], v[172:175], v[208:211], 0
	v_mfma_f32_16x16x32_bf16 v[88:91], v[184:187], v[208:211], 0
	v_mfma_f32_16x16x32_bf16 v[76:79], v[172:175], v[216:219], 0
	v_mfma_f32_16x16x32_bf16 v[68:71], v[184:187], v[216:219], 0
	v_mfma_f32_16x16x32_bf16 v[124:127], v[176:179], v[196:199], v[124:127]
	v_mfma_f32_16x16x32_bf16 v[120:123], v[188:191], v[196:199], v[120:123]
	v_mfma_f32_16x16x32_bf16 v[108:111], v[176:179], v[204:207], v[108:111]
	v_mfma_f32_16x16x32_bf16 v[104:107], v[188:191], v[204:207], v[104:107]
	v_mfma_f32_16x16x32_bf16 v[92:95], v[176:179], v[212:215], v[92:95]
	v_mfma_f32_16x16x32_bf16 v[88:91], v[188:191], v[212:215], v[88:91]
	v_mfma_f32_16x16x32_bf16 v[76:79], v[176:179], v[220:223], v[76:79]
	v_mfma_f32_16x16x32_bf16 v[68:71], v[188:191], v[220:223], v[68:71]
	s_setprio 0
	s_barrier
	s_add_i32 s49, s40, s29
	v_lshl_add_u64 v[180:181], s[22:23], 0, v[130:131]
	s_mov_b32 m0, s49
	ds_read_b128 v[192:195], v157 offset:16384
	ds_read_b128 v[196:199], v157 offset:17408
	ds_read_b128 v[200:203], v157 offset:18432
	ds_read_b128 v[204:207], v157 offset:19456
	ds_read_b128 v[208:211], v157 offset:20480
	ds_read_b128 v[212:215], v157 offset:21504
	ds_read_b128 v[216:219], v157 offset:22528
	ds_read_b128 v[220:223], v157 offset:23552
	global_load_lds_dwordx4 v[180:181], off
	s_add_i32 m0, s49, 0x2000
	s_add_u32 s50, s22, 0x80000
	v_lshl_add_u64 v[224:225], s[22:23], 0, v[134:135]
	s_addc_u32 s51, s23, 0
	s_add_i32 s49, s41, s29
	global_load_lds_dwordx4 v[224:225], off
	v_lshl_add_u64 v[226:227], s[50:51], 0, v[130:131]
	s_mov_b32 m0, s49
	v_lshl_add_u64 v[228:229], s[24:25], 0, v[132:133]
	global_load_lds_dwordx4 v[226:227], off
	v_lshl_add_u64 v[226:227], s[50:51], 0, v[134:135]
	s_add_i32 m0, s49, 0x2000
	s_nop 0
	global_load_lds_dwordx4 v[226:227], off
	v_lshl_add_u64 v[226:227], s[24:25], 0, v[128:129]
	s_mov_b32 m0, s30
	s_nop 0
	global_load_lds_dwordx4 v[226:227], off
	s_mov_b32 m0, s31
	s_nop 0
	global_load_lds_dwordx4 v[228:229], off
	s_waitcnt vmcnt(8)
	s_waitcnt lgkmcnt(0)
	s_barrier
	s_setprio 1
	s_waitcnt lgkmcnt(0)
	v_mfma_f32_16x16x32_bf16 v[52:55], v[144:147], v[192:195], 0
	v_mfma_f32_16x16x32_bf16 v[48:51], v[164:167], v[192:195], 0
	v_mfma_f32_16x16x32_bf16 v[36:39], v[144:147], v[200:203], 0
	v_mfma_f32_16x16x32_bf16 v[32:35], v[164:167], v[200:203], 0
	v_mfma_f32_16x16x32_bf16 v[20:23], v[144:147], v[208:211], 0
	v_mfma_f32_16x16x32_bf16 v[16:19], v[164:167], v[208:211], 0
	v_mfma_f32_16x16x32_bf16 v[4:7], v[144:147], v[216:219], 0
	v_mfma_f32_16x16x32_bf16 v[0:3], v[164:167], v[216:219], 0
	v_mfma_f32_16x16x32_bf16 v[52:55], v[160:163], v[196:199], v[52:55]
	v_mfma_f32_16x16x32_bf16 v[48:51], v[168:171], v[196:199], v[48:51]
	v_mfma_f32_16x16x32_bf16 v[36:39], v[160:163], v[204:207], v[36:39]
	v_mfma_f32_16x16x32_bf16 v[32:35], v[168:171], v[204:207], v[32:35]
	v_mfma_f32_16x16x32_bf16 v[20:23], v[160:163], v[212:215], v[20:23]
	v_mfma_f32_16x16x32_bf16 v[16:19], v[168:171], v[212:215], v[16:19]
	v_mfma_f32_16x16x32_bf16 v[4:7], v[160:163], v[220:223], v[4:7]
	v_mfma_f32_16x16x32_bf16 v[0:3], v[168:171], v[220:223], v[0:3]
	s_setprio 0
	s_setprio 1
	v_mfma_f32_16x16x32_bf16 v[60:63], v[172:175], v[192:195], 0
	v_mfma_f32_16x16x32_bf16 v[56:59], v[184:187], v[192:195], 0
	v_mfma_f32_16x16x32_bf16 v[44:47], v[172:175], v[200:203], 0
	v_mfma_f32_16x16x32_bf16 v[40:43], v[184:187], v[200:203], 0
	v_mfma_f32_16x16x32_bf16 v[28:31], v[172:175], v[208:211], 0
	v_mfma_f32_16x16x32_bf16 v[24:27], v[184:187], v[208:211], 0
	v_mfma_f32_16x16x32_bf16 v[12:15], v[172:175], v[216:219], 0
	v_mfma_f32_16x16x32_bf16 v[8:11], v[184:187], v[216:219], 0
	v_mfma_f32_16x16x32_bf16 v[60:63], v[176:179], v[196:199], v[60:63]
	v_mfma_f32_16x16x32_bf16 v[56:59], v[188:191], v[196:199], v[56:59]
	v_mfma_f32_16x16x32_bf16 v[44:47], v[176:179], v[204:207], v[44:47]
	v_mfma_f32_16x16x32_bf16 v[40:43], v[188:191], v[204:207], v[40:43]
	v_mfma_f32_16x16x32_bf16 v[28:31], v[176:179], v[212:215], v[28:31]
	v_mfma_f32_16x16x32_bf16 v[24:27], v[188:191], v[212:215], v[24:27]
	v_mfma_f32_16x16x32_bf16 v[12:15], v[176:179], v[220:223], v[12:15]
	v_mfma_f32_16x16x32_bf16 v[8:11], v[188:191], v[220:223], v[8:11]
	s_setprio 0
	s_barrier
	s_add_i32 s49, 0, 0x18000
	v_add_u32_e32 v159, s49, v153
	s_add_i32 s50, 0, 0x1c000
	ds_read_b128 v[144:147], v159
	ds_read_b128 v[160:163], v159 offset:1024
	ds_read_b128 v[164:167], v159 offset:2048
	ds_read_b128 v[168:171], v159 offset:3072
	v_add_u32_e32 v159, s50, v153
	ds_read_b128 v[172:175], v159
	ds_read_b128 v[176:179], v159 offset:1024
	ds_read_b128 v[184:187], v159 offset:2048
	ds_read_b128 v[188:191], v159 offset:3072
	s_add_u32 s24, s24, 0x80000
	s_addc_u32 s25, s25, 0
	s_mov_b32 m0, s33
	v_lshl_add_u64 v[230:231], s[24:25], 0, v[128:129]
	ds_read_b128 v[192:195], v157 offset:32768
	ds_read_b128 v[196:199], v157 offset:33792
	ds_read_b128 v[200:203], v157 offset:34816
	ds_read_b128 v[204:207], v157 offset:35840
	ds_read_b128 v[208:211], v157 offset:36864
	ds_read_b128 v[212:215], v157 offset:37888
	ds_read_b128 v[216:219], v157 offset:38912
	ds_read_b128 v[220:223], v157 offset:39936
	global_load_lds_dwordx4 v[230:231], off
	v_lshl_add_u64 v[230:231], s[24:25], 0, v[132:133]
	s_mov_b32 m0, s34
	s_nop 0
	global_load_lds_dwordx4 v[230:231], off
	s_waitcnt vmcnt(8)
	s_waitcnt lgkmcnt(0)
	s_barrier
	s_setprio 1
	s_waitcnt lgkmcnt(0)
	v_mfma_f32_16x16x32_bf16 v[116:119], v[144:147], v[192:195], v[116:119]
	v_mfma_f32_16x16x32_bf16 v[112:115], v[164:167], v[192:195], v[112:115]
	v_mfma_f32_16x16x32_bf16 v[100:103], v[144:147], v[200:203], v[100:103]
	v_mfma_f32_16x16x32_bf16 v[96:99], v[164:167], v[200:203], v[96:99]
	v_mfma_f32_16x16x32_bf16 v[84:87], v[144:147], v[208:211], v[84:87]
	v_mfma_f32_16x16x32_bf16 v[80:83], v[164:167], v[208:211], v[80:83]
	v_mfma_f32_16x16x32_bf16 v[72:75], v[144:147], v[216:219], v[72:75]
	v_mfma_f32_16x16x32_bf16 v[64:67], v[164:167], v[216:219], v[64:67]
	v_mfma_f32_16x16x32_bf16 v[116:119], v[160:163], v[196:199], v[116:119]
	v_mfma_f32_16x16x32_bf16 v[112:115], v[168:171], v[196:199], v[112:115]
	v_mfma_f32_16x16x32_bf16 v[100:103], v[160:163], v[204:207], v[100:103]
	v_mfma_f32_16x16x32_bf16 v[96:99], v[168:171], v[204:207], v[96:99]
	v_mfma_f32_16x16x32_bf16 v[84:87], v[160:163], v[212:215], v[84:87]
	v_mfma_f32_16x16x32_bf16 v[80:83], v[168:171], v[212:215], v[80:83]
	v_mfma_f32_16x16x32_bf16 v[72:75], v[160:163], v[220:223], v[72:75]
	v_mfma_f32_16x16x32_bf16 v[64:67], v[168:171], v[220:223], v[64:67]
	s_setprio 0
	s_setprio 1
	v_mfma_f32_16x16x32_bf16 v[124:127], v[172:175], v[192:195], v[124:127]
	v_mfma_f32_16x16x32_bf16 v[120:123], v[184:187], v[192:195], v[120:123]
	v_mfma_f32_16x16x32_bf16 v[108:111], v[172:175], v[200:203], v[108:111]
	v_mfma_f32_16x16x32_bf16 v[104:107], v[184:187], v[200:203], v[104:107]
	v_mfma_f32_16x16x32_bf16 v[92:95], v[172:175], v[208:211], v[92:95]
	v_mfma_f32_16x16x32_bf16 v[88:91], v[184:187], v[208:211], v[88:91]
	v_mfma_f32_16x16x32_bf16 v[76:79], v[172:175], v[216:219], v[76:79]
	v_mfma_f32_16x16x32_bf16 v[68:71], v[184:187], v[216:219], v[68:71]
	v_mfma_f32_16x16x32_bf16 v[124:127], v[176:179], v[196:199], v[124:127]
	v_mfma_f32_16x16x32_bf16 v[120:123], v[188:191], v[196:199], v[120:123]
	v_mfma_f32_16x16x32_bf16 v[108:111], v[176:179], v[204:207], v[108:111]
	v_mfma_f32_16x16x32_bf16 v[104:107], v[188:191], v[204:207], v[104:107]
	v_mfma_f32_16x16x32_bf16 v[92:95], v[176:179], v[212:215], v[92:95]
	v_mfma_f32_16x16x32_bf16 v[88:91], v[188:191], v[212:215], v[88:91]
	v_mfma_f32_16x16x32_bf16 v[76:79], v[176:179], v[220:223], v[76:79]
	v_mfma_f32_16x16x32_bf16 v[68:71], v[188:191], v[220:223], v[68:71]
	s_setprio 0
	s_barrier
	s_add_i32 s24, s49, s29
	v_lshl_add_u64 v[180:181], v[180:181], 0, s[8:9]
	s_mov_b32 m0, s24
	ds_read_b128 v[192:195], v157 offset:49152
	ds_read_b128 v[196:199], v157 offset:50176
	ds_read_b128 v[200:203], v157 offset:51200
	ds_read_b128 v[204:207], v157 offset:52224
	ds_read_b128 v[208:211], v157 offset:53248
	ds_read_b128 v[212:215], v157 offset:54272
	ds_read_b128 v[216:219], v157 offset:55296
	ds_read_b128 v[220:223], v157 offset:56320
	global_load_lds_dwordx4 v[180:181], off
	s_add_i32 m0, s24, 0x2000
	s_add_u32 s22, s22, 0x80080
	v_lshl_add_u64 v[180:181], v[224:225], 0, s[8:9]
	s_addc_u32 s23, s23, 0
	s_add_i32 s24, s50, s29
	global_load_lds_dwordx4 v[180:181], off
	v_lshl_add_u64 v[180:181], s[22:23], 0, v[130:131]
	s_mov_b32 m0, s24
	s_nop 0
	global_load_lds_dwordx4 v[180:181], off
	v_lshl_add_u64 v[180:181], s[22:23], 0, v[134:135]
	s_add_i32 m0, s24, 0x2000
	s_nop 0
	global_load_lds_dwordx4 v[180:181], off
	v_lshl_add_u64 v[180:181], v[226:227], 0, s[8:9]
	s_mov_b32 m0, s36
	s_nop 0
	global_load_lds_dwordx4 v[180:181], off
	v_lshl_add_u64 v[180:181], v[228:229], 0, s[8:9]
	s_mov_b32 m0, s37
	s_nop 0
	global_load_lds_dwordx4 v[180:181], off
	s_waitcnt vmcnt(8)
	s_waitcnt lgkmcnt(0)
	s_barrier
	s_setprio 1
	s_waitcnt lgkmcnt(0)
	v_mfma_f32_16x16x32_bf16 v[52:55], v[144:147], v[192:195], v[52:55]
	v_mfma_f32_16x16x32_bf16 v[48:51], v[164:167], v[192:195], v[48:51]
	v_mfma_f32_16x16x32_bf16 v[36:39], v[144:147], v[200:203], v[36:39]
	v_mfma_f32_16x16x32_bf16 v[32:35], v[164:167], v[200:203], v[32:35]
	v_mfma_f32_16x16x32_bf16 v[20:23], v[144:147], v[208:211], v[20:23]
	v_mfma_f32_16x16x32_bf16 v[16:19], v[164:167], v[208:211], v[16:19]
	v_mfma_f32_16x16x32_bf16 v[4:7], v[144:147], v[216:219], v[4:7]
	v_mfma_f32_16x16x32_bf16 v[0:3], v[164:167], v[216:219], v[0:3]
	v_mfma_f32_16x16x32_bf16 v[52:55], v[160:163], v[196:199], v[52:55]
	v_mfma_f32_16x16x32_bf16 v[48:51], v[168:171], v[196:199], v[48:51]
	v_mfma_f32_16x16x32_bf16 v[36:39], v[160:163], v[204:207], v[36:39]
	v_mfma_f32_16x16x32_bf16 v[32:35], v[168:171], v[204:207], v[32:35]
	v_mfma_f32_16x16x32_bf16 v[20:23], v[160:163], v[212:215], v[20:23]
	v_mfma_f32_16x16x32_bf16 v[16:19], v[168:171], v[212:215], v[16:19]
	v_mfma_f32_16x16x32_bf16 v[4:7], v[160:163], v[220:223], v[4:7]
	v_mfma_f32_16x16x32_bf16 v[0:3], v[168:171], v[220:223], v[0:3]
	s_setprio 0
	s_setprio 1
	v_mfma_f32_16x16x32_bf16 v[60:63], v[172:175], v[192:195], v[60:63]
	v_mfma_f32_16x16x32_bf16 v[56:59], v[184:187], v[192:195], v[56:59]
	s_add_i32 s48, s48, 2
	s_add_u32 s20, s20, 0x100
	s_addc_u32 s21, s21, 0
	s_add_u32 s46, s46, 0x100
	s_addc_u32 s47, s47, 0
	s_cmp_gt_u32 s48, 29
	v_mfma_f32_16x16x32_bf16 v[44:47], v[172:175], v[200:203], v[44:47]
	v_mfma_f32_16x16x32_bf16 v[40:43], v[184:187], v[200:203], v[40:43]
	v_mfma_f32_16x16x32_bf16 v[28:31], v[172:175], v[208:211], v[28:31]
	v_mfma_f32_16x16x32_bf16 v[24:27], v[184:187], v[208:211], v[24:27]
	v_mfma_f32_16x16x32_bf16 v[12:15], v[172:175], v[216:219], v[12:15]
	v_mfma_f32_16x16x32_bf16 v[8:11], v[184:187], v[216:219], v[8:11]
	v_mfma_f32_16x16x32_bf16 v[60:63], v[176:179], v[196:199], v[60:63]
	v_mfma_f32_16x16x32_bf16 v[56:59], v[188:191], v[196:199], v[56:59]
	v_mfma_f32_16x16x32_bf16 v[44:47], v[176:179], v[204:207], v[44:47]
	v_mfma_f32_16x16x32_bf16 v[40:43], v[188:191], v[204:207], v[40:43]
	v_mfma_f32_16x16x32_bf16 v[28:31], v[176:179], v[212:215], v[28:31]
	v_mfma_f32_16x16x32_bf16 v[24:27], v[188:191], v[212:215], v[24:27]
	v_mfma_f32_16x16x32_bf16 v[12:15], v[176:179], v[220:223], v[12:15]
	v_mfma_f32_16x16x32_bf16 v[8:11], v[188:191], v[220:223], v[8:11]
	s_setprio 0
	s_barrier

.LBB0_2392:
	s_add_u32 s44, s20, 0x100
	s_addc_u32 s45, s21, 0
	s_mov_b32 s46, -2
	s_waitcnt lgkmcnt(0)
	ds_read_b128 v[140:143], v147
	ds_read_b128 v[154:157], v147 offset:1024
	ds_read_b128 v[158:161], v147 offset:2048
	ds_read_b128 v[162:165], v147 offset:3072
	ds_read_b128 v[166:169], v152
	ds_read_b128 v[170:173], v152 offset:1024
	ds_read_b128 v[174:177], v152 offset:2048
	ds_read_b128 v[178:181], v152 offset:3072
	s_add_u32 s20, s18, 0x100
	s_addc_u32 s21, s19, 0
	s_cmpk_eq_i32 s46, 0x54
	s_cselect_b32 s25, s1, s21
	s_cselect_b32 s24, s0, s20
	s_cselect_b32 s23, s17, s45
	s_cselect_b32 s22, s16, s44
	v_lshl_add_u64 v[216:217], s[18:19], 0, v[132:133]
	s_add_i32 m0, s27, 0xc000
	ds_read_b128 v[184:187], v153
	ds_read_b128 v[188:191], v153 offset:1024
	ds_read_b128 v[192:195], v153 offset:2048
	ds_read_b128 v[196:199], v153 offset:3072
	ds_read_b128 v[200:203], v153 offset:4096
	ds_read_b128 v[204:207], v153 offset:5120
	ds_read_b128 v[208:211], v153 offset:6144
	ds_read_b128 v[212:215], v153 offset:7168
	global_load_lds_dwordx4 v[216:217], off
	v_lshl_add_u64 v[216:217], s[18:19], 0, v[134:135]
	s_add_i32 m0, s27, 0xe000
	s_nop 0
	global_load_lds_dwordx4 v[216:217], off
	s_waitcnt vmcnt(8)
	s_waitcnt lgkmcnt(0)
	s_barrier
	s_setprio 1
	s_waitcnt lgkmcnt(0)
	v_mfma_f32_16x16x32_bf16 v[124:127], v[140:143], v[184:187], 0
	v_mfma_f32_16x16x32_bf16 v[120:123], v[158:161], v[184:187], 0
	v_mfma_f32_16x16x32_bf16 v[108:111], v[140:143], v[192:195], 0
	v_mfma_f32_16x16x32_bf16 v[104:107], v[158:161], v[192:195], 0
	v_mfma_f32_16x16x32_bf16 v[92:95], v[140:143], v[200:203], 0
	v_mfma_f32_16x16x32_bf16 v[88:91], v[158:161], v[200:203], 0
	v_mfma_f32_16x16x32_bf16 v[76:79], v[140:143], v[208:211], 0
	v_mfma_f32_16x16x32_bf16 v[72:75], v[158:161], v[208:211], 0
	v_mfma_f32_16x16x32_bf16 v[124:127], v[154:157], v[188:191], v[124:127]
	v_mfma_f32_16x16x32_bf16 v[120:123], v[162:165], v[188:191], v[120:123]
	v_mfma_f32_16x16x32_bf16 v[108:111], v[154:157], v[196:199], v[108:111]
	v_mfma_f32_16x16x32_bf16 v[104:107], v[162:165], v[196:199], v[104:107]
	v_mfma_f32_16x16x32_bf16 v[92:95], v[154:157], v[204:207], v[92:95]
	v_mfma_f32_16x16x32_bf16 v[88:91], v[162:165], v[204:207], v[88:91]
	v_mfma_f32_16x16x32_bf16 v[76:79], v[154:157], v[212:215], v[76:79]
	v_mfma_f32_16x16x32_bf16 v[72:75], v[162:165], v[212:215], v[72:75]
	s_setprio 0
	s_setprio 1
	v_mfma_f32_16x16x32_bf16 v[116:119], v[166:169], v[184:187], 0
	v_mfma_f32_16x16x32_bf16 v[112:115], v[174:177], v[184:187], 0
	v_mfma_f32_16x16x32_bf16 v[100:103], v[166:169], v[192:195], 0
	v_mfma_f32_16x16x32_bf16 v[96:99], v[174:177], v[192:195], 0
	v_mfma_f32_16x16x32_bf16 v[84:87], v[166:169], v[200:203], 0
	v_mfma_f32_16x16x32_bf16 v[80:83], v[174:177], v[200:203], 0
	v_mfma_f32_16x16x32_bf16 v[68:71], v[166:169], v[208:211], 0
	v_mfma_f32_16x16x32_bf16 v[64:67], v[174:177], v[208:211], 0
	v_mfma_f32_16x16x32_bf16 v[116:119], v[170:173], v[188:191], v[116:119]
	v_mfma_f32_16x16x32_bf16 v[112:115], v[178:181], v[188:191], v[112:115]
	v_mfma_f32_16x16x32_bf16 v[100:103], v[170:173], v[196:199], v[100:103]
	v_mfma_f32_16x16x32_bf16 v[96:99], v[178:181], v[196:199], v[96:99]
	v_mfma_f32_16x16x32_bf16 v[84:87], v[170:173], v[204:207], v[84:87]
	v_mfma_f32_16x16x32_bf16 v[80:83], v[178:181], v[204:207], v[80:83]
	v_mfma_f32_16x16x32_bf16 v[68:71], v[170:173], v[212:215], v[68:71]
	v_mfma_f32_16x16x32_bf16 v[64:67], v[178:181], v[212:215], v[64:67]
	s_setprio 0
	s_barrier
	s_add_i32 s18, s38, s26
	v_lshl_add_u64 v[216:217], s[22:23], 0, v[128:129]
	s_mov_b32 m0, s18
	ds_read_b128 v[184:187], v153 offset:16384
	ds_read_b128 v[188:191], v153 offset:17408
	ds_read_b128 v[192:195], v153 offset:18432
	ds_read_b128 v[196:199], v153 offset:19456
	ds_read_b128 v[200:203], v153 offset:20480
	ds_read_b128 v[204:207], v153 offset:21504
	ds_read_b128 v[208:211], v153 offset:22528
	ds_read_b128 v[212:215], v153 offset:23552
	global_load_lds_dwordx4 v[216:217], off
	s_add_i32 m0, s18, 0x2000
	s_add_u32 s18, s22, 0x160000
	v_lshl_add_u64 v[218:219], s[22:23], 0, v[130:131]
	s_addc_u32 s19, s23, 0
	s_add_i32 s47, s39, s26
	global_load_lds_dwordx4 v[218:219], off
	v_lshl_add_u64 v[220:221], s[18:19], 0, v[128:129]
	s_mov_b32 m0, s47
	v_lshl_add_u64 v[222:223], s[24:25], 0, v[130:131]
	global_load_lds_dwordx4 v[220:221], off
	v_lshl_add_u64 v[220:221], s[18:19], 0, v[130:131]
	s_add_i32 m0, s47, 0x2000
	s_nop 0
	global_load_lds_dwordx4 v[220:221], off
	v_lshl_add_u64 v[220:221], s[24:25], 0, v[128:129]
	s_mov_b32 m0, s27
	s_nop 0
	global_load_lds_dwordx4 v[220:221], off
	s_mov_b32 m0, s28
	s_nop 0
	global_load_lds_dwordx4 v[222:223], off
	s_waitcnt vmcnt(8)
	s_waitcnt lgkmcnt(0)
	s_barrier
	s_setprio 1
	s_waitcnt lgkmcnt(0)
	v_mfma_f32_16x16x32_bf16 v[60:63], v[140:143], v[184:187], 0
	v_mfma_f32_16x16x32_bf16 v[56:59], v[158:161], v[184:187], 0
	v_mfma_f32_16x16x32_bf16 v[44:47], v[140:143], v[192:195], 0
	v_mfma_f32_16x16x32_bf16 v[40:43], v[158:161], v[192:195], 0
	v_mfma_f32_16x16x32_bf16 v[28:31], v[140:143], v[200:203], 0
	v_mfma_f32_16x16x32_bf16 v[24:27], v[158:161], v[200:203], 0
	v_mfma_f32_16x16x32_bf16 v[12:15], v[140:143], v[208:211], 0
	v_mfma_f32_16x16x32_bf16 v[8:11], v[158:161], v[208:211], 0
	v_mfma_f32_16x16x32_bf16 v[60:63], v[154:157], v[188:191], v[60:63]
	v_mfma_f32_16x16x32_bf16 v[56:59], v[162:165], v[188:191], v[56:59]
	v_mfma_f32_16x16x32_bf16 v[44:47], v[154:157], v[196:199], v[44:47]
	v_mfma_f32_16x16x32_bf16 v[40:43], v[162:165], v[196:199], v[40:43]
	v_mfma_f32_16x16x32_bf16 v[28:31], v[154:157], v[204:207], v[28:31]
	v_mfma_f32_16x16x32_bf16 v[24:27], v[162:165], v[204:207], v[24:27]
	v_mfma_f32_16x16x32_bf16 v[12:15], v[154:157], v[212:215], v[12:15]
	v_mfma_f32_16x16x32_bf16 v[8:11], v[162:165], v[212:215], v[8:11]
	s_setprio 0
	s_setprio 1
	v_mfma_f32_16x16x32_bf16 v[52:55], v[166:169], v[184:187], 0
	v_mfma_f32_16x16x32_bf16 v[48:51], v[174:177], v[184:187], 0
	v_mfma_f32_16x16x32_bf16 v[36:39], v[166:169], v[192:195], 0
	v_mfma_f32_16x16x32_bf16 v[32:35], v[174:177], v[192:195], 0
	v_mfma_f32_16x16x32_bf16 v[20:23], v[166:169], v[200:203], 0
	v_mfma_f32_16x16x32_bf16 v[16:19], v[174:177], v[200:203], 0
	v_mfma_f32_16x16x32_bf16 v[4:7], v[166:169], v[208:211], 0
	v_mfma_f32_16x16x32_bf16 v[0:3], v[174:177], v[208:211], 0
	v_mfma_f32_16x16x32_bf16 v[52:55], v[170:173], v[188:191], v[52:55]
	v_mfma_f32_16x16x32_bf16 v[48:51], v[178:181], v[188:191], v[48:51]
	v_mfma_f32_16x16x32_bf16 v[36:39], v[170:173], v[196:199], v[36:39]
	v_mfma_f32_16x16x32_bf16 v[32:35], v[178:181], v[196:199], v[32:35]
	v_mfma_f32_16x16x32_bf16 v[20:23], v[170:173], v[204:207], v[20:23]
	v_mfma_f32_16x16x32_bf16 v[16:19], v[178:181], v[204:207], v[16:19]
	v_mfma_f32_16x16x32_bf16 v[4:7], v[170:173], v[212:215], v[4:7]
	v_mfma_f32_16x16x32_bf16 v[0:3], v[178:181], v[212:215], v[0:3]
	s_setprio 0
	s_barrier
	s_add_i32 s47, 0, 0x18000
	s_add_i32 s48, 0, 0x1c000
	v_add_u32_e32 v162, s47, v145
	v_add_u32_e32 v178, s48, v145
	ds_read_b128 v[140:143], v162
	ds_read_b128 v[154:157], v162 offset:1024
	ds_read_b128 v[158:161], v162 offset:2048
	ds_read_b128 v[162:165], v162 offset:3072
	ds_read_b128 v[166:169], v178
	ds_read_b128 v[170:173], v178 offset:1024
	ds_read_b128 v[174:177], v178 offset:2048
	ds_read_b128 v[178:181], v178 offset:3072
	s_add_u32 s18, s24, 0x160000
	s_addc_u32 s19, s25, 0
	s_mov_b32 m0, s29
	v_lshl_add_u64 v[224:225], s[18:19], 0, v[128:129]
	ds_read_b128 v[184:187], v153 offset:32768
	ds_read_b128 v[188:191], v153 offset:33792
	ds_read_b128 v[192:195], v153 offset:34816
	ds_read_b128 v[196:199], v153 offset:35840
	ds_read_b128 v[200:203], v153 offset:36864
	ds_read_b128 v[204:207], v153 offset:37888
	ds_read_b128 v[208:211], v153 offset:38912
	ds_read_b128 v[212:215], v153 offset:39936
	global_load_lds_dwordx4 v[224:225], off
	v_lshl_add_u64 v[224:225], s[18:19], 0, v[130:131]
	s_mov_b32 m0, s30
	s_nop 0
	global_load_lds_dwordx4 v[224:225], off
	s_waitcnt vmcnt(8)
	s_waitcnt lgkmcnt(0)
	s_barrier
	s_setprio 1
	s_waitcnt lgkmcnt(0)
	v_mfma_f32_16x16x32_bf16 v[124:127], v[140:143], v[184:187], v[124:127]
	v_mfma_f32_16x16x32_bf16 v[120:123], v[158:161], v[184:187], v[120:123]
	v_mfma_f32_16x16x32_bf16 v[108:111], v[140:143], v[192:195], v[108:111]
	v_mfma_f32_16x16x32_bf16 v[104:107], v[158:161], v[192:195], v[104:107]
	v_mfma_f32_16x16x32_bf16 v[92:95], v[140:143], v[200:203], v[92:95]
	v_mfma_f32_16x16x32_bf16 v[88:91], v[158:161], v[200:203], v[88:91]
	v_mfma_f32_16x16x32_bf16 v[76:79], v[140:143], v[208:211], v[76:79]
	v_mfma_f32_16x16x32_bf16 v[72:75], v[158:161], v[208:211], v[72:75]
	v_mfma_f32_16x16x32_bf16 v[124:127], v[154:157], v[188:191], v[124:127]
	v_mfma_f32_16x16x32_bf16 v[120:123], v[162:165], v[188:191], v[120:123]
	v_mfma_f32_16x16x32_bf16 v[108:111], v[154:157], v[196:199], v[108:111]
	v_mfma_f32_16x16x32_bf16 v[104:107], v[162:165], v[196:199], v[104:107]
	v_mfma_f32_16x16x32_bf16 v[92:95], v[154:157], v[204:207], v[92:95]
	v_mfma_f32_16x16x32_bf16 v[88:91], v[162:165], v[204:207], v[88:91]
	v_mfma_f32_16x16x32_bf16 v[76:79], v[154:157], v[212:215], v[76:79]
	v_mfma_f32_16x16x32_bf16 v[72:75], v[162:165], v[212:215], v[72:75]
	s_setprio 0
	s_setprio 1
	v_mfma_f32_16x16x32_bf16 v[116:119], v[166:169], v[184:187], v[116:119]
	v_mfma_f32_16x16x32_bf16 v[112:115], v[174:177], v[184:187], v[112:115]
	v_mfma_f32_16x16x32_bf16 v[100:103], v[166:169], v[192:195], v[100:103]
	v_mfma_f32_16x16x32_bf16 v[96:99], v[174:177], v[192:195], v[96:99]
	v_mfma_f32_16x16x32_bf16 v[84:87], v[166:169], v[200:203], v[84:87]
	v_mfma_f32_16x16x32_bf16 v[80:83], v[174:177], v[200:203], v[80:83]
	v_mfma_f32_16x16x32_bf16 v[68:71], v[166:169], v[208:211], v[68:71]
	v_mfma_f32_16x16x32_bf16 v[64:67], v[174:177], v[208:211], v[64:67]
	v_mfma_f32_16x16x32_bf16 v[116:119], v[170:173], v[188:191], v[116:119]
	v_mfma_f32_16x16x32_bf16 v[112:115], v[178:181], v[188:191], v[112:115]
	v_mfma_f32_16x16x32_bf16 v[100:103], v[170:173], v[196:199], v[100:103]
	v_mfma_f32_16x16x32_bf16 v[96:99], v[178:181], v[196:199], v[96:99]
	v_mfma_f32_16x16x32_bf16 v[84:87], v[170:173], v[204:207], v[84:87]
	v_mfma_f32_16x16x32_bf16 v[80:83], v[178:181], v[204:207], v[80:83]
	v_mfma_f32_16x16x32_bf16 v[68:71], v[170:173], v[212:215], v[68:71]
	v_mfma_f32_16x16x32_bf16 v[64:67], v[178:181], v[212:215], v[64:67]
	s_setprio 0
	s_barrier
	s_add_i32 s18, s47, s26
	v_lshl_add_u64 v[216:217], v[216:217], 0, s[12:13]
	s_mov_b32 m0, s18
	ds_read_b128 v[184:187], v153 offset:49152
	ds_read_b128 v[188:191], v153 offset:50176
	ds_read_b128 v[192:195], v153 offset:51200
	ds_read_b128 v[196:199], v153 offset:52224
	ds_read_b128 v[200:203], v153 offset:53248
	ds_read_b128 v[204:207], v153 offset:54272
	ds_read_b128 v[208:211], v153 offset:55296
	ds_read_b128 v[212:215], v153 offset:56320
	global_load_lds_dwordx4 v[216:217], off
	s_add_i32 m0, s18, 0x2000
	s_add_u32 s18, s22, 0x160080
	v_lshl_add_u64 v[216:217], v[218:219], 0, s[12:13]
	s_addc_u32 s19, s23, 0
	s_add_i32 s22, s48, s26
	global_load_lds_dwordx4 v[216:217], off
	v_lshl_add_u64 v[216:217], s[18:19], 0, v[128:129]
	s_mov_b32 m0, s22
	s_nop 0
	global_load_lds_dwordx4 v[216:217], off
	v_lshl_add_u64 v[216:217], s[18:19], 0, v[130:131]
	s_add_i32 m0, s22, 0x2000
	s_nop 0
	global_load_lds_dwordx4 v[216:217], off
	v_lshl_add_u64 v[216:217], v[220:221], 0, s[12:13]
	s_mov_b32 m0, s33
	s_nop 0
	global_load_lds_dwordx4 v[216:217], off
	v_lshl_add_u64 v[216:217], v[222:223], 0, s[12:13]
	s_mov_b32 m0, s34
	s_nop 0
	global_load_lds_dwordx4 v[216:217], off
	s_waitcnt vmcnt(8)
	s_waitcnt lgkmcnt(0)
	s_barrier
	s_setprio 1
	s_waitcnt lgkmcnt(0)
	v_mfma_f32_16x16x32_bf16 v[60:63], v[140:143], v[184:187], v[60:63]
	v_mfma_f32_16x16x32_bf16 v[56:59], v[158:161], v[184:187], v[56:59]
	v_mfma_f32_16x16x32_bf16 v[44:47], v[140:143], v[192:195], v[44:47]
	v_mfma_f32_16x16x32_bf16 v[40:43], v[158:161], v[192:195], v[40:43]
	v_mfma_f32_16x16x32_bf16 v[28:31], v[140:143], v[200:203], v[28:31]
	v_mfma_f32_16x16x32_bf16 v[24:27], v[158:161], v[200:203], v[24:27]
	v_mfma_f32_16x16x32_bf16 v[12:15], v[140:143], v[208:211], v[12:15]
	v_mfma_f32_16x16x32_bf16 v[8:11], v[158:161], v[208:211], v[8:11]
	v_mfma_f32_16x16x32_bf16 v[60:63], v[154:157], v[188:191], v[60:63]
	v_mfma_f32_16x16x32_bf16 v[56:59], v[162:165], v[188:191], v[56:59]
	v_mfma_f32_16x16x32_bf16 v[44:47], v[154:157], v[196:199], v[44:47]
	v_mfma_f32_16x16x32_bf16 v[40:43], v[162:165], v[196:199], v[40:43]
	v_mfma_f32_16x16x32_bf16 v[28:31], v[154:157], v[204:207], v[28:31]
	v_mfma_f32_16x16x32_bf16 v[24:27], v[162:165], v[204:207], v[24:27]
	v_mfma_f32_16x16x32_bf16 v[12:15], v[154:157], v[212:215], v[12:15]
	v_mfma_f32_16x16x32_bf16 v[8:11], v[162:165], v[212:215], v[8:11]
	s_setprio 0
	s_setprio 1
	v_mfma_f32_16x16x32_bf16 v[52:55], v[166:169], v[184:187], v[52:55]
	v_mfma_f32_16x16x32_bf16 v[48:51], v[174:177], v[184:187], v[48:51]
	s_add_i32 s46, s46, 2
	s_add_u32 s44, s44, 0x100
	s_addc_u32 s45, s45, 0
	s_cmpk_gt_u32 s46, 0x55
	s_mov_b64 s[18:19], s[20:21]
	v_mfma_f32_16x16x32_bf16 v[36:39], v[166:169], v[192:195], v[36:39]
	v_mfma_f32_16x16x32_bf16 v[32:35], v[174:177], v[192:195], v[32:35]
	v_mfma_f32_16x16x32_bf16 v[20:23], v[166:169], v[200:203], v[20:23]
	v_mfma_f32_16x16x32_bf16 v[16:19], v[174:177], v[200:203], v[16:19]
	v_mfma_f32_16x16x32_bf16 v[4:7], v[166:169], v[208:211], v[4:7]
	v_mfma_f32_16x16x32_bf16 v[0:3], v[174:177], v[208:211], v[0:3]
	v_mfma_f32_16x16x32_bf16 v[52:55], v[170:173], v[188:191], v[52:55]
	v_mfma_f32_16x16x32_bf16 v[48:51], v[178:181], v[188:191], v[48:51]
	v_mfma_f32_16x16x32_bf16 v[36:39], v[170:173], v[196:199], v[36:39]
	v_mfma_f32_16x16x32_bf16 v[32:35], v[178:181], v[196:199], v[32:35]
	v_mfma_f32_16x16x32_bf16 v[20:23], v[170:173], v[204:207], v[20:23]
	v_mfma_f32_16x16x32_bf16 v[16:19], v[178:181], v[204:207], v[16:19]
	v_mfma_f32_16x16x32_bf16 v[4:7], v[170:173], v[212:215], v[4:7]
	v_mfma_f32_16x16x32_bf16 v[0:3], v[178:181], v[212:215], v[0:3]
	s_setprio 0
	s_barrier
